# sample attention QK^T: 32 K rows in flight + DPP butterfly transpose-reduce (33 ops per head instead of 16x branchy reductions), on top of the S5 y^T + prefetch version
# baseline (speedup 1.0000x reference)
.LBB0_1546:
	v_readlane_b32 s49, v114, 0
	v_readlane_b32 s48, v115, 0
	v_readlane_b32 s51, v114, 1
	v_readlane_b32 s50, v115, 1
	s_nop 2
	global_load_dwordx4 v[72:75], v101, s[48:49]
	s_nop 1
	global_load_dwordx4 v[68:71], v101, s[50:51]
	v_readlane_b32 s49, v114, 2
	v_readlane_b32 s48, v115, 2
	v_readlane_b32 s51, v114, 3
	v_readlane_b32 s50, v115, 3
	s_nop 2
	global_load_dwordx4 v[64:67], v101, s[48:49]
	s_nop 1
	global_load_dwordx4 v[60:63], v101, s[50:51]
	v_readlane_b32 s49, v114, 4
	v_readlane_b32 s48, v115, 4
	v_readlane_b32 s51, v114, 5
	v_readlane_b32 s50, v115, 5
	s_nop 2
	global_load_dwordx4 v[56:59], v101, s[48:49]
	s_nop 1
	global_load_dwordx4 v[52:55], v101, s[50:51]
	v_readlane_b32 s49, v114, 6
	v_readlane_b32 s48, v115, 6
	v_readlane_b32 s51, v114, 7
	v_readlane_b32 s50, v115, 7
	s_nop 2
	global_load_dwordx4 v[48:51], v101, s[48:49]
	s_nop 1
	global_load_dwordx4 v[44:47], v101, s[50:51]
	v_readlane_b32 s49, v114, 8
	v_readlane_b32 s48, v115, 8
	v_readlane_b32 s51, v114, 9
	v_readlane_b32 s50, v115, 9
	s_nop 2
	global_load_dwordx4 v[40:43], v101, s[48:49]
	s_nop 1
	global_load_dwordx4 v[36:39], v101, s[50:51]
	v_readlane_b32 s49, v114, 10
	v_readlane_b32 s48, v115, 10
	v_readlane_b32 s51, v114, 11
	v_readlane_b32 s50, v115, 11
	s_nop 2
	global_load_dwordx4 v[32:35], v101, s[48:49]
	s_nop 1
	global_load_dwordx4 v[28:31], v101, s[50:51]
	v_readlane_b32 s49, v114, 12
	v_readlane_b32 s48, v115, 12
	v_readlane_b32 s51, v114, 13
	v_readlane_b32 s50, v115, 13
	s_nop 2
	global_load_dwordx4 v[24:27], v101, s[48:49]
	s_nop 1
	global_load_dwordx4 v[20:23], v101, s[50:51]
	v_readlane_b32 s49, v114, 14
	v_readlane_b32 s48, v115, 14
	v_readlane_b32 s51, v114, 15
	v_readlane_b32 s50, v115, 15
	s_nop 2
	global_load_dwordx4 v[16:19], v101, s[48:49]
	s_nop 1
	global_load_dwordx4 v[12:15], v101, s[50:51]
	v_readlane_b32 s49, v114, 16
	v_readlane_b32 s48, v115, 16
	v_readlane_b32 s51, v114, 17
	v_readlane_b32 s50, v115, 17
	s_nop 2
	global_load_dwordx4 v[160:163], v101, s[48:49]
	s_nop 1
	global_load_dwordx4 v[164:167], v101, s[50:51]
	v_readlane_b32 s49, v114, 18
	v_readlane_b32 s48, v115, 18
	v_readlane_b32 s51, v114, 19
	v_readlane_b32 s50, v115, 19
	s_nop 2
	global_load_dwordx4 v[168:171], v101, s[48:49]
	s_nop 1
	global_load_dwordx4 v[172:175], v101, s[50:51]
	v_readlane_b32 s49, v114, 20
	v_readlane_b32 s48, v115, 20
	v_readlane_b32 s51, v114, 21
	v_readlane_b32 s50, v115, 21
	s_nop 2
	global_load_dwordx4 v[176:179], v101, s[48:49]
	s_nop 1
	global_load_dwordx4 v[180:183], v101, s[50:51]
	v_readlane_b32 s49, v114, 22
	v_readlane_b32 s48, v115, 22
	v_readlane_b32 s51, v114, 23
	v_readlane_b32 s50, v115, 23
	s_nop 2
	global_load_dwordx4 v[184:187], v101, s[48:49]
	s_nop 1
	global_load_dwordx4 v[188:191], v101, s[50:51]
	v_readlane_b32 s49, v114, 24
	v_readlane_b32 s48, v115, 24
	v_readlane_b32 s51, v114, 25
	v_readlane_b32 s50, v115, 25
	s_nop 2
	global_load_dwordx4 v[192:195], v101, s[48:49]
	s_nop 1
	global_load_dwordx4 v[200:203], v101, s[50:51]
	v_readlane_b32 s49, v114, 26
	v_readlane_b32 s48, v115, 26
	v_readlane_b32 s51, v114, 27
	v_readlane_b32 s50, v115, 27
	s_nop 2
	global_load_dwordx4 v[204:207], v101, s[48:49]
	s_nop 1
	global_load_dwordx4 v[208:211], v101, s[50:51]
	v_readlane_b32 s49, v114, 28
	v_readlane_b32 s48, v115, 28
	v_readlane_b32 s51, v114, 29
	v_readlane_b32 s50, v115, 29
	s_nop 2
	global_load_dwordx4 v[212:215], v101, s[48:49]
	s_nop 1
	global_load_dwordx4 v[216:219], v101, s[50:51]
	v_readlane_b32 s49, v114, 30
	v_readlane_b32 s48, v115, 30
	v_readlane_b32 s51, v114, 31
	v_readlane_b32 s50, v115, 31
	s_nop 2
	global_load_dwordx4 v[220:223], v101, s[48:49]
	s_nop 1
	global_load_dwordx4 v[224:227], v101, s[50:51]
	s_mov_b32 s48, 0xcccccccc
	s_mov_b32 s49, 0xcccccccc
	s_mov_b32 s50, 0xaaaaaaaa
	s_mov_b32 s51, 0xaaaaaaaa
	s_waitcnt vmcnt(28)
	v_mul_f32_e32 v228, v73, v90
	v_mul_f32_e32 v229, v69, v90
	v_mul_f32_e32 v230, v65, v90
	v_mul_f32_e32 v231, v61, v90
	v_fmac_f32_e32 v228, v72, v81
	v_fmac_f32_e32 v229, v68, v81
	v_fmac_f32_e32 v230, v64, v81
	v_fmac_f32_e32 v231, v60, v81
	v_fmac_f32_e32 v228, v74, v91
	v_fmac_f32_e32 v229, v70, v91
	v_fmac_f32_e32 v230, v66, v91
	v_fmac_f32_e32 v231, v62, v91
	v_fmac_f32_e32 v228, v75, v92
	v_fmac_f32_e32 v229, v71, v92
	v_fmac_f32_e32 v230, v67, v92
	v_fmac_f32_e32 v231, v63, v92
	s_waitcnt vmcnt(24)
	v_mul_f32_e32 v232, v57, v90
	v_mul_f32_e32 v233, v53, v90
	v_mul_f32_e32 v234, v49, v90
	v_mul_f32_e32 v235, v45, v90
	v_fmac_f32_e32 v232, v56, v81
	v_fmac_f32_e32 v233, v52, v81
	v_fmac_f32_e32 v234, v48, v81
	v_fmac_f32_e32 v235, v44, v81
	v_fmac_f32_e32 v232, v58, v91
	v_fmac_f32_e32 v233, v54, v91
	v_fmac_f32_e32 v234, v50, v91
	v_fmac_f32_e32 v235, v46, v91
	v_fmac_f32_e32 v232, v59, v92
	v_fmac_f32_e32 v233, v55, v92
	v_fmac_f32_e32 v234, v51, v92
	v_fmac_f32_e32 v235, v47, v92
	s_waitcnt vmcnt(20)
	v_mul_f32_e32 v236, v41, v90
	v_mul_f32_e32 v237, v37, v90
	v_mul_f32_e32 v238, v33, v90
	v_mul_f32_e32 v239, v29, v90
	v_fmac_f32_e32 v236, v40, v81
	v_fmac_f32_e32 v237, v36, v81
	v_fmac_f32_e32 v238, v32, v81
	v_fmac_f32_e32 v239, v28, v81
	v_fmac_f32_e32 v236, v42, v91
	v_fmac_f32_e32 v237, v38, v91
	v_fmac_f32_e32 v238, v34, v91
	v_fmac_f32_e32 v239, v30, v91
	v_fmac_f32_e32 v236, v43, v92
	v_fmac_f32_e32 v237, v39, v92
	v_fmac_f32_e32 v238, v35, v92
	v_fmac_f32_e32 v239, v31, v92
	s_waitcnt vmcnt(16)
	v_mul_f32_e32 v240, v25, v90
	v_mul_f32_e32 v241, v21, v90
	v_mul_f32_e32 v242, v17, v90
	v_mul_f32_e32 v243, v13, v90
	v_fmac_f32_e32 v240, v24, v81
	v_fmac_f32_e32 v241, v20, v81
	v_fmac_f32_e32 v242, v16, v81
	v_fmac_f32_e32 v243, v12, v81
	v_fmac_f32_e32 v240, v26, v91
	v_fmac_f32_e32 v241, v22, v91
	v_fmac_f32_e32 v242, v18, v91
	v_fmac_f32_e32 v243, v14, v91
	v_fmac_f32_e32 v240, v27, v92
	v_fmac_f32_e32 v241, v23, v92
	v_fmac_f32_e32 v242, v19, v92
	v_fmac_f32_e32 v243, v15, v92
	v_add_f32_dpp v228, v228, v228 row_ror:8 row_mask:0xf bank_mask:0x3
	v_add_f32_dpp v229, v229, v229 row_ror:8 row_mask:0xf bank_mask:0x3
	v_add_f32_dpp v230, v230, v230 row_ror:8 row_mask:0xf bank_mask:0x3
	v_add_f32_dpp v231, v231, v231 row_ror:8 row_mask:0xf bank_mask:0x3
	v_add_f32_dpp v232, v232, v232 row_ror:8 row_mask:0xf bank_mask:0x3
	v_add_f32_dpp v233, v233, v233 row_ror:8 row_mask:0xf bank_mask:0x3
	v_add_f32_dpp v234, v234, v234 row_ror:8 row_mask:0xf bank_mask:0x3
	v_add_f32_dpp v235, v235, v235 row_ror:8 row_mask:0xf bank_mask:0x3
	v_add_f32_dpp v228, v236, v236 row_ror:8 row_mask:0xf bank_mask:0xc
	v_add_f32_dpp v229, v237, v237 row_ror:8 row_mask:0xf bank_mask:0xc
	v_add_f32_dpp v230, v238, v238 row_ror:8 row_mask:0xf bank_mask:0xc
	v_add_f32_dpp v231, v239, v239 row_ror:8 row_mask:0xf bank_mask:0xc
	v_add_f32_dpp v232, v240, v240 row_ror:8 row_mask:0xf bank_mask:0xc
	v_add_f32_dpp v233, v241, v241 row_ror:8 row_mask:0xf bank_mask:0xc
	v_add_f32_dpp v234, v242, v242 row_ror:8 row_mask:0xf bank_mask:0xc
	v_add_f32_dpp v235, v243, v243 row_ror:8 row_mask:0xf bank_mask:0xc
	v_add_f32_dpp v228, v228, v228 row_half_mirror row_mask:0xf bank_mask:0x5
	v_add_f32_dpp v229, v229, v229 row_half_mirror row_mask:0xf bank_mask:0x5
	v_add_f32_dpp v230, v230, v230 row_half_mirror row_mask:0xf bank_mask:0x5
	v_add_f32_dpp v231, v231, v231 row_half_mirror row_mask:0xf bank_mask:0x5
	v_add_f32_dpp v228, v232, v232 row_half_mirror row_mask:0xf bank_mask:0xa
	v_add_f32_dpp v229, v233, v233 row_half_mirror row_mask:0xf bank_mask:0xa
	v_add_f32_dpp v230, v234, v234 row_half_mirror row_mask:0xf bank_mask:0xa
	v_add_f32_dpp v231, v235, v235 row_half_mirror row_mask:0xf bank_mask:0xa
	v_add_f32_dpp v244, v228, v228 quad_perm:[2,3,0,1] row_mask:0xf bank_mask:0xf
	v_add_f32_dpp v245, v229, v229 quad_perm:[2,3,0,1] row_mask:0xf bank_mask:0xf
	v_add_f32_dpp v246, v230, v230 quad_perm:[2,3,0,1] row_mask:0xf bank_mask:0xf
	v_add_f32_dpp v247, v231, v231 quad_perm:[2,3,0,1] row_mask:0xf bank_mask:0xf
	v_cndmask_b32_e64 v228, v244, v246, s[48:49]
	v_cndmask_b32_e64 v229, v245, v247, s[48:49]
	s_nop 0
	v_add_f32_dpp v244, v228, v228 quad_perm:[1,0,3,2] row_mask:0xf bank_mask:0xf
	v_add_f32_dpp v245, v229, v229 quad_perm:[1,0,3,2] row_mask:0xf bank_mask:0xf
	v_cndmask_b32_e64 v4, v244, v245, s[50:51]
	v_mul_f32_e32 v228, v73, v103
	v_mul_f32_e32 v229, v69, v103
	v_mul_f32_e32 v230, v65, v103
	v_mul_f32_e32 v231, v61, v103
	v_fmac_f32_e32 v228, v72, v93
	v_fmac_f32_e32 v229, v68, v93
	v_fmac_f32_e32 v230, v64, v93
	v_fmac_f32_e32 v231, v60, v93
	v_fmac_f32_e32 v228, v74, v104
	v_fmac_f32_e32 v229, v70, v104
	v_fmac_f32_e32 v230, v66, v104
	v_fmac_f32_e32 v231, v62, v104
	v_fmac_f32_e32 v228, v75, v105
	v_fmac_f32_e32 v229, v71, v105
	v_fmac_f32_e32 v230, v67, v105
	v_fmac_f32_e32 v231, v63, v105
	v_mul_f32_e32 v232, v57, v103
	v_mul_f32_e32 v233, v53, v103
	v_mul_f32_e32 v234, v49, v103
	v_mul_f32_e32 v235, v45, v103
	v_fmac_f32_e32 v232, v56, v93
	v_fmac_f32_e32 v233, v52, v93
	v_fmac_f32_e32 v234, v48, v93
	v_fmac_f32_e32 v235, v44, v93
	v_fmac_f32_e32 v232, v58, v104
	v_fmac_f32_e32 v233, v54, v104
	v_fmac_f32_e32 v234, v50, v104
	v_fmac_f32_e32 v235, v46, v104
	v_fmac_f32_e32 v232, v59, v105
	v_fmac_f32_e32 v233, v55, v105
	v_fmac_f32_e32 v234, v51, v105
	v_fmac_f32_e32 v235, v47, v105
	v_mul_f32_e32 v236, v41, v103
	v_mul_f32_e32 v237, v37, v103
	v_mul_f32_e32 v238, v33, v103
	v_mul_f32_e32 v239, v29, v103
	v_fmac_f32_e32 v236, v40, v93
	v_fmac_f32_e32 v237, v36, v93
	v_fmac_f32_e32 v238, v32, v93
	v_fmac_f32_e32 v239, v28, v93
	v_fmac_f32_e32 v236, v42, v104
	v_fmac_f32_e32 v237, v38, v104
	v_fmac_f32_e32 v238, v34, v104
	v_fmac_f32_e32 v239, v30, v104
	v_fmac_f32_e32 v236, v43, v105
	v_fmac_f32_e32 v237, v39, v105
	v_fmac_f32_e32 v238, v35, v105
	v_fmac_f32_e32 v239, v31, v105
	v_mul_f32_e32 v240, v25, v103
	v_mul_f32_e32 v241, v21, v103
	v_mul_f32_e32 v242, v17, v103
	v_mul_f32_e32 v243, v13, v103
	v_fmac_f32_e32 v240, v24, v93
	v_fmac_f32_e32 v241, v20, v93
	v_fmac_f32_e32 v242, v16, v93
	v_fmac_f32_e32 v243, v12, v93
	v_fmac_f32_e32 v240, v26, v104
	v_fmac_f32_e32 v241, v22, v104
	v_fmac_f32_e32 v242, v18, v104
	v_fmac_f32_e32 v243, v14, v104
	v_fmac_f32_e32 v240, v27, v105
	v_fmac_f32_e32 v241, v23, v105
	v_fmac_f32_e32 v242, v19, v105
	v_fmac_f32_e32 v243, v15, v105
	v_add_f32_dpp v228, v228, v228 row_ror:8 row_mask:0xf bank_mask:0x3
	v_add_f32_dpp v229, v229, v229 row_ror:8 row_mask:0xf bank_mask:0x3
	v_add_f32_dpp v230, v230, v230 row_ror:8 row_mask:0xf bank_mask:0x3
	v_add_f32_dpp v231, v231, v231 row_ror:8 row_mask:0xf bank_mask:0x3
	v_add_f32_dpp v232, v232, v232 row_ror:8 row_mask:0xf bank_mask:0x3
	v_add_f32_dpp v233, v233, v233 row_ror:8 row_mask:0xf bank_mask:0x3
	v_add_f32_dpp v234, v234, v234 row_ror:8 row_mask:0xf bank_mask:0x3
	v_add_f32_dpp v235, v235, v235 row_ror:8 row_mask:0xf bank_mask:0x3
	v_add_f32_dpp v228, v236, v236 row_ror:8 row_mask:0xf bank_mask:0xc
	v_add_f32_dpp v229, v237, v237 row_ror:8 row_mask:0xf bank_mask:0xc
	v_add_f32_dpp v230, v238, v238 row_ror:8 row_mask:0xf bank_mask:0xc
	v_add_f32_dpp v231, v239, v239 row_ror:8 row_mask:0xf bank_mask:0xc
	v_add_f32_dpp v232, v240, v240 row_ror:8 row_mask:0xf bank_mask:0xc
	v_add_f32_dpp v233, v241, v241 row_ror:8 row_mask:0xf bank_mask:0xc
	v_add_f32_dpp v234, v242, v242 row_ror:8 row_mask:0xf bank_mask:0xc
	v_add_f32_dpp v235, v243, v243 row_ror:8 row_mask:0xf bank_mask:0xc
	v_add_f32_dpp v228, v228, v228 row_half_mirror row_mask:0xf bank_mask:0x5
	v_add_f32_dpp v229, v229, v229 row_half_mirror row_mask:0xf bank_mask:0x5
	v_add_f32_dpp v230, v230, v230 row_half_mirror row_mask:0xf bank_mask:0x5
	v_add_f32_dpp v231, v231, v231 row_half_mirror row_mask:0xf bank_mask:0x5
	v_add_f32_dpp v228, v232, v232 row_half_mirror row_mask:0xf bank_mask:0xa
	v_add_f32_dpp v229, v233, v233 row_half_mirror row_mask:0xf bank_mask:0xa
	v_add_f32_dpp v230, v234, v234 row_half_mirror row_mask:0xf bank_mask:0xa
	v_add_f32_dpp v231, v235, v235 row_half_mirror row_mask:0xf bank_mask:0xa
	v_add_f32_dpp v244, v228, v228 quad_perm:[2,3,0,1] row_mask:0xf bank_mask:0xf
	v_add_f32_dpp v245, v229, v229 quad_perm:[2,3,0,1] row_mask:0xf bank_mask:0xf
	v_add_f32_dpp v246, v230, v230 quad_perm:[2,3,0,1] row_mask:0xf bank_mask:0xf
	v_add_f32_dpp v247, v231, v231 quad_perm:[2,3,0,1] row_mask:0xf bank_mask:0xf
	v_cndmask_b32_e64 v228, v244, v246, s[48:49]
	v_cndmask_b32_e64 v229, v245, v247, s[48:49]
	s_nop 0
	v_add_f32_dpp v244, v228, v228 quad_perm:[1,0,3,2] row_mask:0xf bank_mask:0xf
	v_add_f32_dpp v245, v229, v229 quad_perm:[1,0,3,2] row_mask:0xf bank_mask:0xf
	v_cndmask_b32_e64 v6, v244, v245, s[50:51]
	v_mul_f32_e32 v228, v73, v107
	v_mul_f32_e32 v229, v69, v107
	v_mul_f32_e32 v230, v65, v107
	v_mul_f32_e32 v231, v61, v107
	v_fmac_f32_e32 v228, v72, v106
	v_fmac_f32_e32 v229, v68, v106
	v_fmac_f32_e32 v230, v64, v106
	v_fmac_f32_e32 v231, v60, v106
	v_fmac_f32_e32 v228, v74, v108
	v_fmac_f32_e32 v229, v70, v108
	v_fmac_f32_e32 v230, v66, v108
	v_fmac_f32_e32 v231, v62, v108
	v_fmac_f32_e32 v228, v75, v109
	v_fmac_f32_e32 v229, v71, v109
	v_fmac_f32_e32 v230, v67, v109
	v_fmac_f32_e32 v231, v63, v109
	v_mul_f32_e32 v232, v57, v107
	v_mul_f32_e32 v233, v53, v107
	v_mul_f32_e32 v234, v49, v107
	v_mul_f32_e32 v235, v45, v107
	v_fmac_f32_e32 v232, v56, v106
	v_fmac_f32_e32 v233, v52, v106
	v_fmac_f32_e32 v234, v48, v106
	v_fmac_f32_e32 v235, v44, v106
	v_fmac_f32_e32 v232, v58, v108
	v_fmac_f32_e32 v233, v54, v108
	v_fmac_f32_e32 v234, v50, v108
	v_fmac_f32_e32 v235, v46, v108
	v_fmac_f32_e32 v232, v59, v109
	v_fmac_f32_e32 v233, v55, v109
	v_fmac_f32_e32 v234, v51, v109
	v_fmac_f32_e32 v235, v47, v109
	v_mul_f32_e32 v236, v41, v107
	v_mul_f32_e32 v237, v37, v107
	v_mul_f32_e32 v238, v33, v107
	v_mul_f32_e32 v239, v29, v107
	v_fmac_f32_e32 v236, v40, v106
	v_fmac_f32_e32 v237, v36, v106
	v_fmac_f32_e32 v238, v32, v106
	v_fmac_f32_e32 v239, v28, v106
	v_fmac_f32_e32 v236, v42, v108
	v_fmac_f32_e32 v237, v38, v108
	v_fmac_f32_e32 v238, v34, v108
	v_fmac_f32_e32 v239, v30, v108
	v_fmac_f32_e32 v236, v43, v109
	v_fmac_f32_e32 v237, v39, v109
	v_fmac_f32_e32 v238, v35, v109
	v_fmac_f32_e32 v239, v31, v109
	v_mul_f32_e32 v240, v25, v107
	v_mul_f32_e32 v241, v21, v107
	v_mul_f32_e32 v242, v17, v107
	v_mul_f32_e32 v243, v13, v107
	v_fmac_f32_e32 v240, v24, v106
	v_fmac_f32_e32 v241, v20, v106
	v_fmac_f32_e32 v242, v16, v106
	v_fmac_f32_e32 v243, v12, v106
	v_fmac_f32_e32 v240, v26, v108
	v_fmac_f32_e32 v241, v22, v108
	v_fmac_f32_e32 v242, v18, v108
	v_fmac_f32_e32 v243, v14, v108
	v_fmac_f32_e32 v240, v27, v109
	v_fmac_f32_e32 v241, v23, v109
	v_fmac_f32_e32 v242, v19, v109
	v_fmac_f32_e32 v243, v15, v109
	v_add_f32_dpp v228, v228, v228 row_ror:8 row_mask:0xf bank_mask:0x3
	v_add_f32_dpp v229, v229, v229 row_ror:8 row_mask:0xf bank_mask:0x3
	v_add_f32_dpp v230, v230, v230 row_ror:8 row_mask:0xf bank_mask:0x3
	v_add_f32_dpp v231, v231, v231 row_ror:8 row_mask:0xf bank_mask:0x3
	v_add_f32_dpp v232, v232, v232 row_ror:8 row_mask:0xf bank_mask:0x3
	v_add_f32_dpp v233, v233, v233 row_ror:8 row_mask:0xf bank_mask:0x3
	v_add_f32_dpp v234, v234, v234 row_ror:8 row_mask:0xf bank_mask:0x3
	v_add_f32_dpp v235, v235, v235 row_ror:8 row_mask:0xf bank_mask:0x3
	v_add_f32_dpp v228, v236, v236 row_ror:8 row_mask:0xf bank_mask:0xc
	v_add_f32_dpp v229, v237, v237 row_ror:8 row_mask:0xf bank_mask:0xc
	v_add_f32_dpp v230, v238, v238 row_ror:8 row_mask:0xf bank_mask:0xc
	v_add_f32_dpp v231, v239, v239 row_ror:8 row_mask:0xf bank_mask:0xc
	v_add_f32_dpp v232, v240, v240 row_ror:8 row_mask:0xf bank_mask:0xc
	v_add_f32_dpp v233, v241, v241 row_ror:8 row_mask:0xf bank_mask:0xc
	v_add_f32_dpp v234, v242, v242 row_ror:8 row_mask:0xf bank_mask:0xc
	v_add_f32_dpp v235, v243, v243 row_ror:8 row_mask:0xf bank_mask:0xc
	v_add_f32_dpp v228, v228, v228 row_half_mirror row_mask:0xf bank_mask:0x5
	v_add_f32_dpp v229, v229, v229 row_half_mirror row_mask:0xf bank_mask:0x5
	v_add_f32_dpp v230, v230, v230 row_half_mirror row_mask:0xf bank_mask:0x5
	v_add_f32_dpp v231, v231, v231 row_half_mirror row_mask:0xf bank_mask:0x5
	v_add_f32_dpp v228, v232, v232 row_half_mirror row_mask:0xf bank_mask:0xa
	v_add_f32_dpp v229, v233, v233 row_half_mirror row_mask:0xf bank_mask:0xa
	v_add_f32_dpp v230, v234, v234 row_half_mirror row_mask:0xf bank_mask:0xa
	v_add_f32_dpp v231, v235, v235 row_half_mirror row_mask:0xf bank_mask:0xa
	v_add_f32_dpp v244, v228, v228 quad_perm:[2,3,0,1] row_mask:0xf bank_mask:0xf
	v_add_f32_dpp v245, v229, v229 quad_perm:[2,3,0,1] row_mask:0xf bank_mask:0xf
	v_add_f32_dpp v246, v230, v230 quad_perm:[2,3,0,1] row_mask:0xf bank_mask:0xf
	v_add_f32_dpp v247, v231, v231 quad_perm:[2,3,0,1] row_mask:0xf bank_mask:0xf
	v_cndmask_b32_e64 v228, v244, v246, s[48:49]
	v_cndmask_b32_e64 v229, v245, v247, s[48:49]
	s_nop 0
	v_add_f32_dpp v244, v228, v228 quad_perm:[1,0,3,2] row_mask:0xf bank_mask:0xf
	v_add_f32_dpp v245, v229, v229 quad_perm:[1,0,3,2] row_mask:0xf bank_mask:0xf
	v_cndmask_b32_e64 v8, v244, v245, s[50:51]
	v_mul_f32_e32 v228, v73, v111
	v_mul_f32_e32 v229, v69, v111
	v_mul_f32_e32 v230, v65, v111
	v_mul_f32_e32 v231, v61, v111
	v_fmac_f32_e32 v228, v72, v110
	v_fmac_f32_e32 v229, v68, v110
	v_fmac_f32_e32 v230, v64, v110
	v_fmac_f32_e32 v231, v60, v110
	v_fmac_f32_e32 v228, v74, v112
	v_fmac_f32_e32 v229, v70, v112
	v_fmac_f32_e32 v230, v66, v112
	v_fmac_f32_e32 v231, v62, v112
	v_fmac_f32_e32 v228, v75, v113
	v_fmac_f32_e32 v229, v71, v113
	v_fmac_f32_e32 v230, v67, v113
	v_fmac_f32_e32 v231, v63, v113
	v_mul_f32_e32 v232, v57, v111
	v_mul_f32_e32 v233, v53, v111
	v_mul_f32_e32 v234, v49, v111
	v_mul_f32_e32 v235, v45, v111
	v_fmac_f32_e32 v232, v56, v110
	v_fmac_f32_e32 v233, v52, v110
	v_fmac_f32_e32 v234, v48, v110
	v_fmac_f32_e32 v235, v44, v110
	v_fmac_f32_e32 v232, v58, v112
	v_fmac_f32_e32 v233, v54, v112
	v_fmac_f32_e32 v234, v50, v112
	v_fmac_f32_e32 v235, v46, v112
	v_fmac_f32_e32 v232, v59, v113
	v_fmac_f32_e32 v233, v55, v113
	v_fmac_f32_e32 v234, v51, v113
	v_fmac_f32_e32 v235, v47, v113
	v_mul_f32_e32 v236, v41, v111
	v_mul_f32_e32 v237, v37, v111
	v_mul_f32_e32 v238, v33, v111
	v_mul_f32_e32 v239, v29, v111
	v_fmac_f32_e32 v236, v40, v110
	v_fmac_f32_e32 v237, v36, v110
	v_fmac_f32_e32 v238, v32, v110
	v_fmac_f32_e32 v239, v28, v110
	v_fmac_f32_e32 v236, v42, v112
	v_fmac_f32_e32 v237, v38, v112
	v_fmac_f32_e32 v238, v34, v112
	v_fmac_f32_e32 v239, v30, v112
	v_fmac_f32_e32 v236, v43, v113
	v_fmac_f32_e32 v237, v39, v113
	v_fmac_f32_e32 v238, v35, v113
	v_fmac_f32_e32 v239, v31, v113
	v_mul_f32_e32 v240, v25, v111
	v_mul_f32_e32 v241, v21, v111
	v_mul_f32_e32 v242, v17, v111
	v_mul_f32_e32 v243, v13, v111
	v_fmac_f32_e32 v240, v24, v110
	v_fmac_f32_e32 v241, v20, v110
	v_fmac_f32_e32 v242, v16, v110
	v_fmac_f32_e32 v243, v12, v110
	v_fmac_f32_e32 v240, v26, v112
	v_fmac_f32_e32 v241, v22, v112
	v_fmac_f32_e32 v242, v18, v112
	v_fmac_f32_e32 v243, v14, v112
	v_fmac_f32_e32 v240, v27, v113
	v_fmac_f32_e32 v241, v23, v113
	v_fmac_f32_e32 v242, v19, v113
	v_fmac_f32_e32 v243, v15, v113
	v_add_f32_dpp v228, v228, v228 row_ror:8 row_mask:0xf bank_mask:0x3
	v_add_f32_dpp v229, v229, v229 row_ror:8 row_mask:0xf bank_mask:0x3
	v_add_f32_dpp v230, v230, v230 row_ror:8 row_mask:0xf bank_mask:0x3
	v_add_f32_dpp v231, v231, v231 row_ror:8 row_mask:0xf bank_mask:0x3
	v_add_f32_dpp v232, v232, v232 row_ror:8 row_mask:0xf bank_mask:0x3
	v_add_f32_dpp v233, v233, v233 row_ror:8 row_mask:0xf bank_mask:0x3
	v_add_f32_dpp v234, v234, v234 row_ror:8 row_mask:0xf bank_mask:0x3
	v_add_f32_dpp v235, v235, v235 row_ror:8 row_mask:0xf bank_mask:0x3
	v_add_f32_dpp v228, v236, v236 row_ror:8 row_mask:0xf bank_mask:0xc
	v_add_f32_dpp v229, v237, v237 row_ror:8 row_mask:0xf bank_mask:0xc
	v_add_f32_dpp v230, v238, v238 row_ror:8 row_mask:0xf bank_mask:0xc
	v_add_f32_dpp v231, v239, v239 row_ror:8 row_mask:0xf bank_mask:0xc
	v_add_f32_dpp v232, v240, v240 row_ror:8 row_mask:0xf bank_mask:0xc
	v_add_f32_dpp v233, v241, v241 row_ror:8 row_mask:0xf bank_mask:0xc
	v_add_f32_dpp v234, v242, v242 row_ror:8 row_mask:0xf bank_mask:0xc
	v_add_f32_dpp v235, v243, v243 row_ror:8 row_mask:0xf bank_mask:0xc
	v_add_f32_dpp v228, v228, v228 row_half_mirror row_mask:0xf bank_mask:0x5
	v_add_f32_dpp v229, v229, v229 row_half_mirror row_mask:0xf bank_mask:0x5
	v_add_f32_dpp v230, v230, v230 row_half_mirror row_mask:0xf bank_mask:0x5
	v_add_f32_dpp v231, v231, v231 row_half_mirror row_mask:0xf bank_mask:0x5
	v_add_f32_dpp v228, v232, v232 row_half_mirror row_mask:0xf bank_mask:0xa
	v_add_f32_dpp v229, v233, v233 row_half_mirror row_mask:0xf bank_mask:0xa
	v_add_f32_dpp v230, v234, v234 row_half_mirror row_mask:0xf bank_mask:0xa
	v_add_f32_dpp v231, v235, v235 row_half_mirror row_mask:0xf bank_mask:0xa
	v_add_f32_dpp v244, v228, v228 quad_perm:[2,3,0,1] row_mask:0xf bank_mask:0xf
	v_add_f32_dpp v245, v229, v229 quad_perm:[2,3,0,1] row_mask:0xf bank_mask:0xf
	v_add_f32_dpp v246, v230, v230 quad_perm:[2,3,0,1] row_mask:0xf bank_mask:0xf
	v_add_f32_dpp v247, v231, v231 quad_perm:[2,3,0,1] row_mask:0xf bank_mask:0xf
	v_cndmask_b32_e64 v228, v244, v246, s[48:49]
	v_cndmask_b32_e64 v229, v245, v247, s[48:49]
	s_nop 0
	v_add_f32_dpp v244, v228, v228 quad_perm:[1,0,3,2] row_mask:0xf bank_mask:0xf
	v_add_f32_dpp v245, v229, v229 quad_perm:[1,0,3,2] row_mask:0xf bank_mask:0xf
	v_cndmask_b32_e64 v10, v244, v245, s[50:51]
	s_waitcnt vmcnt(12)
	v_mul_f32_e32 v228, v161, v90
	v_mul_f32_e32 v229, v165, v90
	v_mul_f32_e32 v230, v169, v90
	v_mul_f32_e32 v231, v173, v90
	v_fmac_f32_e32 v228, v160, v81
	v_fmac_f32_e32 v229, v164, v81
	v_fmac_f32_e32 v230, v168, v81
	v_fmac_f32_e32 v231, v172, v81
	v_fmac_f32_e32 v228, v162, v91
	v_fmac_f32_e32 v229, v166, v91
	v_fmac_f32_e32 v230, v170, v91
	v_fmac_f32_e32 v231, v174, v91
	v_fmac_f32_e32 v228, v163, v92
	v_fmac_f32_e32 v229, v167, v92
	v_fmac_f32_e32 v230, v171, v92
	v_fmac_f32_e32 v231, v175, v92
	s_waitcnt vmcnt(8)
	v_mul_f32_e32 v232, v177, v90
	v_mul_f32_e32 v233, v181, v90
	v_mul_f32_e32 v234, v185, v90
	v_mul_f32_e32 v235, v189, v90
	v_fmac_f32_e32 v232, v176, v81
	v_fmac_f32_e32 v233, v180, v81
	v_fmac_f32_e32 v234, v184, v81
	v_fmac_f32_e32 v235, v188, v81
	v_fmac_f32_e32 v232, v178, v91
	v_fmac_f32_e32 v233, v182, v91
	v_fmac_f32_e32 v234, v186, v91
	v_fmac_f32_e32 v235, v190, v91
	v_fmac_f32_e32 v232, v179, v92
	v_fmac_f32_e32 v233, v183, v92
	v_fmac_f32_e32 v234, v187, v92
	v_fmac_f32_e32 v235, v191, v92
	s_waitcnt vmcnt(4)
	v_mul_f32_e32 v236, v193, v90
	v_mul_f32_e32 v237, v201, v90
	v_mul_f32_e32 v238, v205, v90
	v_mul_f32_e32 v239, v209, v90
	v_fmac_f32_e32 v236, v192, v81
	v_fmac_f32_e32 v237, v200, v81
	v_fmac_f32_e32 v238, v204, v81
	v_fmac_f32_e32 v239, v208, v81
	v_fmac_f32_e32 v236, v194, v91
	v_fmac_f32_e32 v237, v202, v91
	v_fmac_f32_e32 v238, v206, v91
	v_fmac_f32_e32 v239, v210, v91
	v_fmac_f32_e32 v236, v195, v92
	v_fmac_f32_e32 v237, v203, v92
	v_fmac_f32_e32 v238, v207, v92
	v_fmac_f32_e32 v239, v211, v92
	s_waitcnt vmcnt(0)
	v_mul_f32_e32 v240, v213, v90
	v_mul_f32_e32 v241, v217, v90
	v_mul_f32_e32 v242, v221, v90
	v_mul_f32_e32 v243, v225, v90
	v_fmac_f32_e32 v240, v212, v81
	v_fmac_f32_e32 v241, v216, v81
	v_fmac_f32_e32 v242, v220, v81
	v_fmac_f32_e32 v243, v224, v81
	v_fmac_f32_e32 v240, v214, v91
	v_fmac_f32_e32 v241, v218, v91
	v_fmac_f32_e32 v242, v222, v91
	v_fmac_f32_e32 v243, v226, v91
	v_fmac_f32_e32 v240, v215, v92
	v_fmac_f32_e32 v241, v219, v92
	v_fmac_f32_e32 v242, v223, v92
	v_fmac_f32_e32 v243, v227, v92
	v_add_f32_dpp v228, v228, v228 row_ror:8 row_mask:0xf bank_mask:0x3
	v_add_f32_dpp v229, v229, v229 row_ror:8 row_mask:0xf bank_mask:0x3
	v_add_f32_dpp v230, v230, v230 row_ror:8 row_mask:0xf bank_mask:0x3
	v_add_f32_dpp v231, v231, v231 row_ror:8 row_mask:0xf bank_mask:0x3
	v_add_f32_dpp v232, v232, v232 row_ror:8 row_mask:0xf bank_mask:0x3
	v_add_f32_dpp v233, v233, v233 row_ror:8 row_mask:0xf bank_mask:0x3
	v_add_f32_dpp v234, v234, v234 row_ror:8 row_mask:0xf bank_mask:0x3
	v_add_f32_dpp v235, v235, v235 row_ror:8 row_mask:0xf bank_mask:0x3
	v_add_f32_dpp v228, v236, v236 row_ror:8 row_mask:0xf bank_mask:0xc
	v_add_f32_dpp v229, v237, v237 row_ror:8 row_mask:0xf bank_mask:0xc
	v_add_f32_dpp v230, v238, v238 row_ror:8 row_mask:0xf bank_mask:0xc
	v_add_f32_dpp v231, v239, v239 row_ror:8 row_mask:0xf bank_mask:0xc
	v_add_f32_dpp v232, v240, v240 row_ror:8 row_mask:0xf bank_mask:0xc
	v_add_f32_dpp v233, v241, v241 row_ror:8 row_mask:0xf bank_mask:0xc
	v_add_f32_dpp v234, v242, v242 row_ror:8 row_mask:0xf bank_mask:0xc
	v_add_f32_dpp v235, v243, v243 row_ror:8 row_mask:0xf bank_mask:0xc
	v_add_f32_dpp v228, v228, v228 row_half_mirror row_mask:0xf bank_mask:0x5
	v_add_f32_dpp v229, v229, v229 row_half_mirror row_mask:0xf bank_mask:0x5
	v_add_f32_dpp v230, v230, v230 row_half_mirror row_mask:0xf bank_mask:0x5
	v_add_f32_dpp v231, v231, v231 row_half_mirror row_mask:0xf bank_mask:0x5
	v_add_f32_dpp v228, v232, v232 row_half_mirror row_mask:0xf bank_mask:0xa
	v_add_f32_dpp v229, v233, v233 row_half_mirror row_mask:0xf bank_mask:0xa
	v_add_f32_dpp v230, v234, v234 row_half_mirror row_mask:0xf bank_mask:0xa
	v_add_f32_dpp v231, v235, v235 row_half_mirror row_mask:0xf bank_mask:0xa
	v_add_f32_dpp v244, v228, v228 quad_perm:[2,3,0,1] row_mask:0xf bank_mask:0xf
	v_add_f32_dpp v245, v229, v229 quad_perm:[2,3,0,1] row_mask:0xf bank_mask:0xf
	v_add_f32_dpp v246, v230, v230 quad_perm:[2,3,0,1] row_mask:0xf bank_mask:0xf
	v_add_f32_dpp v247, v231, v231 quad_perm:[2,3,0,1] row_mask:0xf bank_mask:0xf
	v_cndmask_b32_e64 v228, v244, v246, s[48:49]
	v_cndmask_b32_e64 v229, v245, v247, s[48:49]
	s_nop 0
	v_add_f32_dpp v244, v228, v228 quad_perm:[1,0,3,2] row_mask:0xf bank_mask:0xf
	v_add_f32_dpp v245, v229, v229 quad_perm:[1,0,3,2] row_mask:0xf bank_mask:0xf
	v_cndmask_b32_e64 v5, v244, v245, s[50:51]
	v_mul_f32_e32 v228, v161, v103
	v_mul_f32_e32 v229, v165, v103
	v_mul_f32_e32 v230, v169, v103
	v_mul_f32_e32 v231, v173, v103
	v_fmac_f32_e32 v228, v160, v93
	v_fmac_f32_e32 v229, v164, v93
	v_fmac_f32_e32 v230, v168, v93
	v_fmac_f32_e32 v231, v172, v93
	v_fmac_f32_e32 v228, v162, v104
	v_fmac_f32_e32 v229, v166, v104
	v_fmac_f32_e32 v230, v170, v104
	v_fmac_f32_e32 v231, v174, v104
	v_fmac_f32_e32 v228, v163, v105
	v_fmac_f32_e32 v229, v167, v105
	v_fmac_f32_e32 v230, v171, v105
	v_fmac_f32_e32 v231, v175, v105
	v_mul_f32_e32 v232, v177, v103
	v_mul_f32_e32 v233, v181, v103
	v_mul_f32_e32 v234, v185, v103
	v_mul_f32_e32 v235, v189, v103
	v_fmac_f32_e32 v232, v176, v93
	v_fmac_f32_e32 v233, v180, v93
	v_fmac_f32_e32 v234, v184, v93
	v_fmac_f32_e32 v235, v188, v93
	v_fmac_f32_e32 v232, v178, v104
	v_fmac_f32_e32 v233, v182, v104
	v_fmac_f32_e32 v234, v186, v104
	v_fmac_f32_e32 v235, v190, v104
	v_fmac_f32_e32 v232, v179, v105
	v_fmac_f32_e32 v233, v183, v105
	v_fmac_f32_e32 v234, v187, v105
	v_fmac_f32_e32 v235, v191, v105
	v_mul_f32_e32 v236, v193, v103
	v_mul_f32_e32 v237, v201, v103
	v_mul_f32_e32 v238, v205, v103
	v_mul_f32_e32 v239, v209, v103
	v_fmac_f32_e32 v236, v192, v93
	v_fmac_f32_e32 v237, v200, v93
	v_fmac_f32_e32 v238, v204, v93
	v_fmac_f32_e32 v239, v208, v93
	v_fmac_f32_e32 v236, v194, v104
	v_fmac_f32_e32 v237, v202, v104
	v_fmac_f32_e32 v238, v206, v104
	v_fmac_f32_e32 v239, v210, v104
	v_fmac_f32_e32 v236, v195, v105
	v_fmac_f32_e32 v237, v203, v105
	v_fmac_f32_e32 v238, v207, v105
	v_fmac_f32_e32 v239, v211, v105
	v_mul_f32_e32 v240, v213, v103
	v_mul_f32_e32 v241, v217, v103
	v_mul_f32_e32 v242, v221, v103
	v_mul_f32_e32 v243, v225, v103
	v_fmac_f32_e32 v240, v212, v93
	v_fmac_f32_e32 v241, v216, v93
	v_fmac_f32_e32 v242, v220, v93
	v_fmac_f32_e32 v243, v224, v93
	v_fmac_f32_e32 v240, v214, v104
	v_fmac_f32_e32 v241, v218, v104
	v_fmac_f32_e32 v242, v222, v104
	v_fmac_f32_e32 v243, v226, v104
	v_fmac_f32_e32 v240, v215, v105
	v_fmac_f32_e32 v241, v219, v105
	v_fmac_f32_e32 v242, v223, v105
	v_fmac_f32_e32 v243, v227, v105
	v_add_f32_dpp v228, v228, v228 row_ror:8 row_mask:0xf bank_mask:0x3
	v_add_f32_dpp v229, v229, v229 row_ror:8 row_mask:0xf bank_mask:0x3
	v_add_f32_dpp v230, v230, v230 row_ror:8 row_mask:0xf bank_mask:0x3
	v_add_f32_dpp v231, v231, v231 row_ror:8 row_mask:0xf bank_mask:0x3
	v_add_f32_dpp v232, v232, v232 row_ror:8 row_mask:0xf bank_mask:0x3
	v_add_f32_dpp v233, v233, v233 row_ror:8 row_mask:0xf bank_mask:0x3
	v_add_f32_dpp v234, v234, v234 row_ror:8 row_mask:0xf bank_mask:0x3
	v_add_f32_dpp v235, v235, v235 row_ror:8 row_mask:0xf bank_mask:0x3
	v_add_f32_dpp v228, v236, v236 row_ror:8 row_mask:0xf bank_mask:0xc
	v_add_f32_dpp v229, v237, v237 row_ror:8 row_mask:0xf bank_mask:0xc
	v_add_f32_dpp v230, v238, v238 row_ror:8 row_mask:0xf bank_mask:0xc
	v_add_f32_dpp v231, v239, v239 row_ror:8 row_mask:0xf bank_mask:0xc
	v_add_f32_dpp v232, v240, v240 row_ror:8 row_mask:0xf bank_mask:0xc
	v_add_f32_dpp v233, v241, v241 row_ror:8 row_mask:0xf bank_mask:0xc
	v_add_f32_dpp v234, v242, v242 row_ror:8 row_mask:0xf bank_mask:0xc
	v_add_f32_dpp v235, v243, v243 row_ror:8 row_mask:0xf bank_mask:0xc
	v_add_f32_dpp v228, v228, v228 row_half_mirror row_mask:0xf bank_mask:0x5
	v_add_f32_dpp v229, v229, v229 row_half_mirror row_mask:0xf bank_mask:0x5
	v_add_f32_dpp v230, v230, v230 row_half_mirror row_mask:0xf bank_mask:0x5
	v_add_f32_dpp v231, v231, v231 row_half_mirror row_mask:0xf bank_mask:0x5
	v_add_f32_dpp v228, v232, v232 row_half_mirror row_mask:0xf bank_mask:0xa
	v_add_f32_dpp v229, v233, v233 row_half_mirror row_mask:0xf bank_mask:0xa
	v_add_f32_dpp v230, v234, v234 row_half_mirror row_mask:0xf bank_mask:0xa
	v_add_f32_dpp v231, v235, v235 row_half_mirror row_mask:0xf bank_mask:0xa
	v_add_f32_dpp v244, v228, v228 quad_perm:[2,3,0,1] row_mask:0xf bank_mask:0xf
	v_add_f32_dpp v245, v229, v229 quad_perm:[2,3,0,1] row_mask:0xf bank_mask:0xf
	v_add_f32_dpp v246, v230, v230 quad_perm:[2,3,0,1] row_mask:0xf bank_mask:0xf
	v_add_f32_dpp v247, v231, v231 quad_perm:[2,3,0,1] row_mask:0xf bank_mask:0xf
	v_cndmask_b32_e64 v228, v244, v246, s[48:49]
	v_cndmask_b32_e64 v229, v245, v247, s[48:49]
	s_nop 0
	v_add_f32_dpp v244, v228, v228 quad_perm:[1,0,3,2] row_mask:0xf bank_mask:0xf
	v_add_f32_dpp v245, v229, v229 quad_perm:[1,0,3,2] row_mask:0xf bank_mask:0xf
	v_cndmask_b32_e64 v7, v244, v245, s[50:51]
	v_mul_f32_e32 v228, v161, v107
	v_mul_f32_e32 v229, v165, v107
	v_mul_f32_e32 v230, v169, v107
	v_mul_f32_e32 v231, v173, v107
	v_fmac_f32_e32 v228, v160, v106
	v_fmac_f32_e32 v229, v164, v106
	v_fmac_f32_e32 v230, v168, v106
	v_fmac_f32_e32 v231, v172, v106
	v_fmac_f32_e32 v228, v162, v108
	v_fmac_f32_e32 v229, v166, v108
	v_fmac_f32_e32 v230, v170, v108
	v_fmac_f32_e32 v231, v174, v108
	v_fmac_f32_e32 v228, v163, v109
	v_fmac_f32_e32 v229, v167, v109
	v_fmac_f32_e32 v230, v171, v109
	v_fmac_f32_e32 v231, v175, v109
	v_mul_f32_e32 v232, v177, v107
	v_mul_f32_e32 v233, v181, v107
	v_mul_f32_e32 v234, v185, v107
	v_mul_f32_e32 v235, v189, v107
	v_fmac_f32_e32 v232, v176, v106
	v_fmac_f32_e32 v233, v180, v106
	v_fmac_f32_e32 v234, v184, v106
	v_fmac_f32_e32 v235, v188, v106
	v_fmac_f32_e32 v232, v178, v108
	v_fmac_f32_e32 v233, v182, v108
	v_fmac_f32_e32 v234, v186, v108
	v_fmac_f32_e32 v235, v190, v108
	v_fmac_f32_e32 v232, v179, v109
	v_fmac_f32_e32 v233, v183, v109
	v_fmac_f32_e32 v234, v187, v109
	v_fmac_f32_e32 v235, v191, v109
	v_mul_f32_e32 v236, v193, v107
	v_mul_f32_e32 v237, v201, v107
	v_mul_f32_e32 v238, v205, v107
	v_mul_f32_e32 v239, v209, v107
	v_fmac_f32_e32 v236, v192, v106
	v_fmac_f32_e32 v237, v200, v106
	v_fmac_f32_e32 v238, v204, v106
	v_fmac_f32_e32 v239, v208, v106
	v_fmac_f32_e32 v236, v194, v108
	v_fmac_f32_e32 v237, v202, v108
	v_fmac_f32_e32 v238, v206, v108
	v_fmac_f32_e32 v239, v210, v108
	v_fmac_f32_e32 v236, v195, v109
	v_fmac_f32_e32 v237, v203, v109
	v_fmac_f32_e32 v238, v207, v109
	v_fmac_f32_e32 v239, v211, v109
	v_mul_f32_e32 v240, v213, v107
	v_mul_f32_e32 v241, v217, v107
	v_mul_f32_e32 v242, v221, v107
	v_mul_f32_e32 v243, v225, v107
	v_fmac_f32_e32 v240, v212, v106
	v_fmac_f32_e32 v241, v216, v106
	v_fmac_f32_e32 v242, v220, v106
	v_fmac_f32_e32 v243, v224, v106
	v_fmac_f32_e32 v240, v214, v108
	v_fmac_f32_e32 v241, v218, v108
	v_fmac_f32_e32 v242, v222, v108
	v_fmac_f32_e32 v243, v226, v108
	v_fmac_f32_e32 v240, v215, v109
	v_fmac_f32_e32 v241, v219, v109
	v_fmac_f32_e32 v242, v223, v109
	v_fmac_f32_e32 v243, v227, v109
	v_add_f32_dpp v228, v228, v228 row_ror:8 row_mask:0xf bank_mask:0x3
	v_add_f32_dpp v229, v229, v229 row_ror:8 row_mask:0xf bank_mask:0x3
	v_add_f32_dpp v230, v230, v230 row_ror:8 row_mask:0xf bank_mask:0x3
	v_add_f32_dpp v231, v231, v231 row_ror:8 row_mask:0xf bank_mask:0x3
	v_add_f32_dpp v232, v232, v232 row_ror:8 row_mask:0xf bank_mask:0x3
	v_add_f32_dpp v233, v233, v233 row_ror:8 row_mask:0xf bank_mask:0x3
	v_add_f32_dpp v234, v234, v234 row_ror:8 row_mask:0xf bank_mask:0x3
	v_add_f32_dpp v235, v235, v235 row_ror:8 row_mask:0xf bank_mask:0x3
	v_add_f32_dpp v228, v236, v236 row_ror:8 row_mask:0xf bank_mask:0xc
	v_add_f32_dpp v229, v237, v237 row_ror:8 row_mask:0xf bank_mask:0xc
	v_add_f32_dpp v230, v238, v238 row_ror:8 row_mask:0xf bank_mask:0xc
	v_add_f32_dpp v231, v239, v239 row_ror:8 row_mask:0xf bank_mask:0xc
	v_add_f32_dpp v232, v240, v240 row_ror:8 row_mask:0xf bank_mask:0xc
	v_add_f32_dpp v233, v241, v241 row_ror:8 row_mask:0xf bank_mask:0xc
	v_add_f32_dpp v234, v242, v242 row_ror:8 row_mask:0xf bank_mask:0xc
	v_add_f32_dpp v235, v243, v243 row_ror:8 row_mask:0xf bank_mask:0xc
	v_add_f32_dpp v228, v228, v228 row_half_mirror row_mask:0xf bank_mask:0x5
	v_add_f32_dpp v229, v229, v229 row_half_mirror row_mask:0xf bank_mask:0x5
	v_add_f32_dpp v230, v230, v230 row_half_mirror row_mask:0xf bank_mask:0x5
	v_add_f32_dpp v231, v231, v231 row_half_mirror row_mask:0xf bank_mask:0x5
	v_add_f32_dpp v228, v232, v232 row_half_mirror row_mask:0xf bank_mask:0xa
	v_add_f32_dpp v229, v233, v233 row_half_mirror row_mask:0xf bank_mask:0xa
	v_add_f32_dpp v230, v234, v234 row_half_mirror row_mask:0xf bank_mask:0xa
	v_add_f32_dpp v231, v235, v235 row_half_mirror row_mask:0xf bank_mask:0xa
	v_add_f32_dpp v244, v228, v228 quad_perm:[2,3,0,1] row_mask:0xf bank_mask:0xf
	v_add_f32_dpp v245, v229, v229 quad_perm:[2,3,0,1] row_mask:0xf bank_mask:0xf
	v_add_f32_dpp v246, v230, v230 quad_perm:[2,3,0,1] row_mask:0xf bank_mask:0xf
	v_add_f32_dpp v247, v231, v231 quad_perm:[2,3,0,1] row_mask:0xf bank_mask:0xf
	v_cndmask_b32_e64 v228, v244, v246, s[48:49]
	v_cndmask_b32_e64 v229, v245, v247, s[48:49]
	s_nop 0
	v_add_f32_dpp v244, v228, v228 quad_perm:[1,0,3,2] row_mask:0xf bank_mask:0xf
	v_add_f32_dpp v245, v229, v229 quad_perm:[1,0,3,2] row_mask:0xf bank_mask:0xf
	v_cndmask_b32_e64 v9, v244, v245, s[50:51]
	v_mul_f32_e32 v228, v161, v111
	v_mul_f32_e32 v229, v165, v111
	v_mul_f32_e32 v230, v169, v111
	v_mul_f32_e32 v231, v173, v111
	v_fmac_f32_e32 v228, v160, v110
	v_fmac_f32_e32 v229, v164, v110
	v_fmac_f32_e32 v230, v168, v110
	v_fmac_f32_e32 v231, v172, v110
	v_fmac_f32_e32 v228, v162, v112
	v_fmac_f32_e32 v229, v166, v112
	v_fmac_f32_e32 v230, v170, v112
	v_fmac_f32_e32 v231, v174, v112
	v_fmac_f32_e32 v228, v163, v113
	v_fmac_f32_e32 v229, v167, v113
	v_fmac_f32_e32 v230, v171, v113
	v_fmac_f32_e32 v231, v175, v113
	v_mul_f32_e32 v232, v177, v111
	v_mul_f32_e32 v233, v181, v111
	v_mul_f32_e32 v234, v185, v111
	v_mul_f32_e32 v235, v189, v111
	v_fmac_f32_e32 v232, v176, v110
	v_fmac_f32_e32 v233, v180, v110
	v_fmac_f32_e32 v234, v184, v110
	v_fmac_f32_e32 v235, v188, v110
	v_fmac_f32_e32 v232, v178, v112
	v_fmac_f32_e32 v233, v182, v112
	v_fmac_f32_e32 v234, v186, v112
	v_fmac_f32_e32 v235, v190, v112
	v_fmac_f32_e32 v232, v179, v113
	v_fmac_f32_e32 v233, v183, v113
	v_fmac_f32_e32 v234, v187, v113
	v_fmac_f32_e32 v235, v191, v113
	v_mul_f32_e32 v236, v193, v111
	v_mul_f32_e32 v237, v201, v111
	v_mul_f32_e32 v238, v205, v111
	v_mul_f32_e32 v239, v209, v111
	v_fmac_f32_e32 v236, v192, v110
	v_fmac_f32_e32 v237, v200, v110
	v_fmac_f32_e32 v238, v204, v110
	v_fmac_f32_e32 v239, v208, v110
	v_fmac_f32_e32 v236, v194, v112
	v_fmac_f32_e32 v237, v202, v112
	v_fmac_f32_e32 v238, v206, v112
	v_fmac_f32_e32 v239, v210, v112
	v_fmac_f32_e32 v236, v195, v113
	v_fmac_f32_e32 v237, v203, v113
	v_fmac_f32_e32 v238, v207, v113
	v_fmac_f32_e32 v239, v211, v113
	v_mul_f32_e32 v240, v213, v111
	v_mul_f32_e32 v241, v217, v111
	v_mul_f32_e32 v242, v221, v111
	v_mul_f32_e32 v243, v225, v111
	v_fmac_f32_e32 v240, v212, v110
	v_fmac_f32_e32 v241, v216, v110
	v_fmac_f32_e32 v242, v220, v110
	v_fmac_f32_e32 v243, v224, v110
	v_fmac_f32_e32 v240, v214, v112
	v_fmac_f32_e32 v241, v218, v112
	v_fmac_f32_e32 v242, v222, v112
	v_fmac_f32_e32 v243, v226, v112
	v_fmac_f32_e32 v240, v215, v113
	v_fmac_f32_e32 v241, v219, v113
	v_fmac_f32_e32 v242, v223, v113
	v_fmac_f32_e32 v243, v227, v113
	v_add_f32_dpp v228, v228, v228 row_ror:8 row_mask:0xf bank_mask:0x3
	v_add_f32_dpp v229, v229, v229 row_ror:8 row_mask:0xf bank_mask:0x3
	v_add_f32_dpp v230, v230, v230 row_ror:8 row_mask:0xf bank_mask:0x3
	v_add_f32_dpp v231, v231, v231 row_ror:8 row_mask:0xf bank_mask:0x3
	v_add_f32_dpp v232, v232, v232 row_ror:8 row_mask:0xf bank_mask:0x3
	v_add_f32_dpp v233, v233, v233 row_ror:8 row_mask:0xf bank_mask:0x3
	v_add_f32_dpp v234, v234, v234 row_ror:8 row_mask:0xf bank_mask:0x3
	v_add_f32_dpp v235, v235, v235 row_ror:8 row_mask:0xf bank_mask:0x3
	v_add_f32_dpp v228, v236, v236 row_ror:8 row_mask:0xf bank_mask:0xc
	v_add_f32_dpp v229, v237, v237 row_ror:8 row_mask:0xf bank_mask:0xc
	v_add_f32_dpp v230, v238, v238 row_ror:8 row_mask:0xf bank_mask:0xc
	v_add_f32_dpp v231, v239, v239 row_ror:8 row_mask:0xf bank_mask:0xc
	v_add_f32_dpp v232, v240, v240 row_ror:8 row_mask:0xf bank_mask:0xc
	v_add_f32_dpp v233, v241, v241 row_ror:8 row_mask:0xf bank_mask:0xc
	v_add_f32_dpp v234, v242, v242 row_ror:8 row_mask:0xf bank_mask:0xc
	v_add_f32_dpp v235, v243, v243 row_ror:8 row_mask:0xf bank_mask:0xc
	v_add_f32_dpp v228, v228, v228 row_half_mirror row_mask:0xf bank_mask:0x5
	v_add_f32_dpp v229, v229, v229 row_half_mirror row_mask:0xf bank_mask:0x5
	v_add_f32_dpp v230, v230, v230 row_half_mirror row_mask:0xf bank_mask:0x5
	v_add_f32_dpp v231, v231, v231 row_half_mirror row_mask:0xf bank_mask:0x5
	v_add_f32_dpp v228, v232, v232 row_half_mirror row_mask:0xf bank_mask:0xa
	v_add_f32_dpp v229, v233, v233 row_half_mirror row_mask:0xf bank_mask:0xa
	v_add_f32_dpp v230, v234, v234 row_half_mirror row_mask:0xf bank_mask:0xa
	v_add_f32_dpp v231, v235, v235 row_half_mirror row_mask:0xf bank_mask:0xa
	v_add_f32_dpp v244, v228, v228 quad_perm:[2,3,0,1] row_mask:0xf bank_mask:0xf
	v_add_f32_dpp v245, v229, v229 quad_perm:[2,3,0,1] row_mask:0xf bank_mask:0xf
	v_add_f32_dpp v246, v230, v230 quad_perm:[2,3,0,1] row_mask:0xf bank_mask:0xf
	v_add_f32_dpp v247, v231, v231 quad_perm:[2,3,0,1] row_mask:0xf bank_mask:0xf
	v_cndmask_b32_e64 v228, v244, v246, s[48:49]
	v_cndmask_b32_e64 v229, v245, v247, s[48:49]
	s_nop 0
	v_add_f32_dpp v244, v228, v228 quad_perm:[1,0,3,2] row_mask:0xf bank_mask:0xf
	v_add_f32_dpp v245, v229, v229 quad_perm:[1,0,3,2] row_mask:0xf bank_mask:0xf
	v_cndmask_b32_e64 v11, v244, v245, s[50:51]

.LBB0_1979:
	v_readlane_b32 s49, v118, 0
	v_readlane_b32 s48, v119, 0
	v_readlane_b32 s51, v118, 1
	v_readlane_b32 s50, v119, 1
	s_nop 2
	global_load_dwordx4 v[70:73], v97, s[48:49]
	s_nop 1
	global_load_dwordx4 v[66:69], v97, s[50:51]
	v_readlane_b32 s49, v118, 2
	v_readlane_b32 s48, v119, 2
	v_readlane_b32 s51, v118, 3
	v_readlane_b32 s50, v119, 3
	s_nop 2
	global_load_dwordx4 v[62:65], v97, s[48:49]
	s_nop 1
	global_load_dwordx4 v[58:61], v97, s[50:51]
	v_readlane_b32 s49, v118, 4
	v_readlane_b32 s48, v119, 4
	v_readlane_b32 s51, v118, 5
	v_readlane_b32 s50, v119, 5
	s_nop 2
	global_load_dwordx4 v[54:57], v97, s[48:49]
	s_nop 1
	global_load_dwordx4 v[50:53], v97, s[50:51]
	v_readlane_b32 s49, v118, 6
	v_readlane_b32 s48, v119, 6
	v_readlane_b32 s51, v118, 7
	v_readlane_b32 s50, v119, 7
	s_nop 2
	global_load_dwordx4 v[46:49], v97, s[48:49]
	s_nop 1
	global_load_dwordx4 v[42:45], v97, s[50:51]
	v_readlane_b32 s49, v118, 8
	v_readlane_b32 s48, v119, 8
	v_readlane_b32 s51, v118, 9
	v_readlane_b32 s50, v119, 9
	s_nop 2
	global_load_dwordx4 v[38:41], v97, s[48:49]
	s_nop 1
	global_load_dwordx4 v[34:37], v97, s[50:51]
	v_readlane_b32 s49, v118, 10
	v_readlane_b32 s48, v119, 10
	v_readlane_b32 s51, v118, 11
	v_readlane_b32 s50, v119, 11
	s_nop 2
	global_load_dwordx4 v[30:33], v97, s[48:49]
	s_nop 1
	global_load_dwordx4 v[26:29], v97, s[50:51]
	v_readlane_b32 s49, v118, 12
	v_readlane_b32 s48, v119, 12
	v_readlane_b32 s51, v118, 13
	v_readlane_b32 s50, v119, 13
	s_nop 2
	global_load_dwordx4 v[22:25], v97, s[48:49]
	s_nop 1
	global_load_dwordx4 v[18:21], v97, s[50:51]
	v_readlane_b32 s49, v118, 14
	v_readlane_b32 s48, v119, 14
	v_readlane_b32 s51, v118, 15
	v_readlane_b32 s50, v119, 15
	s_nop 2
	global_load_dwordx4 v[14:17], v97, s[48:49]
	s_nop 1
	global_load_dwordx4 v[10:13], v97, s[50:51]
	v_readlane_b32 s49, v118, 16
	v_readlane_b32 s48, v119, 16
	v_readlane_b32 s51, v118, 17
	v_readlane_b32 s50, v119, 17
	s_nop 2
	global_load_dwordx4 v[160:163], v97, s[48:49]
	s_nop 1
	global_load_dwordx4 v[164:167], v97, s[50:51]
	v_readlane_b32 s49, v118, 18
	v_readlane_b32 s48, v119, 18
	v_readlane_b32 s51, v118, 19
	v_readlane_b32 s50, v119, 19
	s_nop 2
	global_load_dwordx4 v[168:171], v97, s[48:49]
	s_nop 1
	global_load_dwordx4 v[172:175], v97, s[50:51]
	v_readlane_b32 s49, v118, 20
	v_readlane_b32 s48, v119, 20
	v_readlane_b32 s51, v118, 21
	v_readlane_b32 s50, v119, 21
	s_nop 2
	global_load_dwordx4 v[176:179], v97, s[48:49]
	s_nop 1
	global_load_dwordx4 v[180:183], v97, s[50:51]
	v_readlane_b32 s49, v118, 22
	v_readlane_b32 s48, v119, 22
	v_readlane_b32 s51, v118, 23
	v_readlane_b32 s50, v119, 23
	s_nop 2
	global_load_dwordx4 v[184:187], v97, s[48:49]
	s_nop 1
	global_load_dwordx4 v[188:191], v97, s[50:51]
	v_readlane_b32 s49, v118, 24
	v_readlane_b32 s48, v119, 24
	v_readlane_b32 s51, v118, 25
	v_readlane_b32 s50, v119, 25
	s_nop 2
	global_load_dwordx4 v[192:195], v97, s[48:49]
	s_nop 1
	global_load_dwordx4 v[200:203], v97, s[50:51]
	v_readlane_b32 s49, v118, 26
	v_readlane_b32 s48, v119, 26
	v_readlane_b32 s51, v118, 27
	v_readlane_b32 s50, v119, 27
	s_nop 2
	global_load_dwordx4 v[204:207], v97, s[48:49]
	s_nop 1
	global_load_dwordx4 v[208:211], v97, s[50:51]
	v_readlane_b32 s49, v118, 28
	v_readlane_b32 s48, v119, 28
	v_readlane_b32 s51, v118, 29
	v_readlane_b32 s50, v119, 29
	s_nop 2
	global_load_dwordx4 v[212:215], v97, s[48:49]
	s_nop 1
	global_load_dwordx4 v[216:219], v97, s[50:51]
	v_readlane_b32 s49, v118, 30
	v_readlane_b32 s48, v119, 30
	v_readlane_b32 s51, v118, 31
	v_readlane_b32 s50, v119, 31
	s_nop 2
	global_load_dwordx4 v[220:223], v97, s[48:49]
	s_nop 1
	global_load_dwordx4 v[224:227], v97, s[50:51]
	s_mov_b32 s48, 0xcccccccc
	s_mov_b32 s49, 0xcccccccc
	s_mov_b32 s50, 0xaaaaaaaa
	s_mov_b32 s51, 0xaaaaaaaa
	s_waitcnt vmcnt(28)
	v_mul_f32_e32 v228, v71, v88
	v_mul_f32_e32 v229, v67, v88
	v_mul_f32_e32 v230, v63, v88
	v_mul_f32_e32 v231, v59, v88
	v_fmac_f32_e32 v228, v70, v79
	v_fmac_f32_e32 v229, v66, v79
	v_fmac_f32_e32 v230, v62, v79
	v_fmac_f32_e32 v231, v58, v79
	v_fmac_f32_e32 v228, v72, v89
	v_fmac_f32_e32 v229, v68, v89
	v_fmac_f32_e32 v230, v64, v89
	v_fmac_f32_e32 v231, v60, v89
	v_fmac_f32_e32 v228, v73, v90
	v_fmac_f32_e32 v229, v69, v90
	v_fmac_f32_e32 v230, v65, v90
	v_fmac_f32_e32 v231, v61, v90
	s_waitcnt vmcnt(24)
	v_mul_f32_e32 v232, v55, v88
	v_mul_f32_e32 v233, v51, v88
	v_mul_f32_e32 v234, v47, v88
	v_mul_f32_e32 v235, v43, v88
	v_fmac_f32_e32 v232, v54, v79
	v_fmac_f32_e32 v233, v50, v79
	v_fmac_f32_e32 v234, v46, v79
	v_fmac_f32_e32 v235, v42, v79
	v_fmac_f32_e32 v232, v56, v89
	v_fmac_f32_e32 v233, v52, v89
	v_fmac_f32_e32 v234, v48, v89
	v_fmac_f32_e32 v235, v44, v89
	v_fmac_f32_e32 v232, v57, v90
	v_fmac_f32_e32 v233, v53, v90
	v_fmac_f32_e32 v234, v49, v90
	v_fmac_f32_e32 v235, v45, v90
	s_waitcnt vmcnt(20)
	v_mul_f32_e32 v236, v39, v88
	v_mul_f32_e32 v237, v35, v88
	v_mul_f32_e32 v238, v31, v88
	v_mul_f32_e32 v239, v27, v88
	v_fmac_f32_e32 v236, v38, v79
	v_fmac_f32_e32 v237, v34, v79
	v_fmac_f32_e32 v238, v30, v79
	v_fmac_f32_e32 v239, v26, v79
	v_fmac_f32_e32 v236, v40, v89
	v_fmac_f32_e32 v237, v36, v89
	v_fmac_f32_e32 v238, v32, v89
	v_fmac_f32_e32 v239, v28, v89
	v_fmac_f32_e32 v236, v41, v90
	v_fmac_f32_e32 v237, v37, v90
	v_fmac_f32_e32 v238, v33, v90
	v_fmac_f32_e32 v239, v29, v90
	s_waitcnt vmcnt(16)
	v_mul_f32_e32 v240, v23, v88
	v_mul_f32_e32 v241, v19, v88
	v_mul_f32_e32 v242, v15, v88
	v_mul_f32_e32 v243, v11, v88
	v_fmac_f32_e32 v240, v22, v79
	v_fmac_f32_e32 v241, v18, v79
	v_fmac_f32_e32 v242, v14, v79
	v_fmac_f32_e32 v243, v10, v79
	v_fmac_f32_e32 v240, v24, v89
	v_fmac_f32_e32 v241, v20, v89
	v_fmac_f32_e32 v242, v16, v89
	v_fmac_f32_e32 v243, v12, v89
	v_fmac_f32_e32 v240, v25, v90
	v_fmac_f32_e32 v241, v21, v90
	v_fmac_f32_e32 v242, v17, v90
	v_fmac_f32_e32 v243, v13, v90
	v_add_f32_dpp v228, v228, v228 row_ror:8 row_mask:0xf bank_mask:0x3
	v_add_f32_dpp v229, v229, v229 row_ror:8 row_mask:0xf bank_mask:0x3
	v_add_f32_dpp v230, v230, v230 row_ror:8 row_mask:0xf bank_mask:0x3
	v_add_f32_dpp v231, v231, v231 row_ror:8 row_mask:0xf bank_mask:0x3
	v_add_f32_dpp v232, v232, v232 row_ror:8 row_mask:0xf bank_mask:0x3
	v_add_f32_dpp v233, v233, v233 row_ror:8 row_mask:0xf bank_mask:0x3
	v_add_f32_dpp v234, v234, v234 row_ror:8 row_mask:0xf bank_mask:0x3
	v_add_f32_dpp v235, v235, v235 row_ror:8 row_mask:0xf bank_mask:0x3
	v_add_f32_dpp v228, v236, v236 row_ror:8 row_mask:0xf bank_mask:0xc
	v_add_f32_dpp v229, v237, v237 row_ror:8 row_mask:0xf bank_mask:0xc
	v_add_f32_dpp v230, v238, v238 row_ror:8 row_mask:0xf bank_mask:0xc
	v_add_f32_dpp v231, v239, v239 row_ror:8 row_mask:0xf bank_mask:0xc
	v_add_f32_dpp v232, v240, v240 row_ror:8 row_mask:0xf bank_mask:0xc
	v_add_f32_dpp v233, v241, v241 row_ror:8 row_mask:0xf bank_mask:0xc
	v_add_f32_dpp v234, v242, v242 row_ror:8 row_mask:0xf bank_mask:0xc
	v_add_f32_dpp v235, v243, v243 row_ror:8 row_mask:0xf bank_mask:0xc
	v_add_f32_dpp v228, v228, v228 row_half_mirror row_mask:0xf bank_mask:0x5
	v_add_f32_dpp v229, v229, v229 row_half_mirror row_mask:0xf bank_mask:0x5
	v_add_f32_dpp v230, v230, v230 row_half_mirror row_mask:0xf bank_mask:0x5
	v_add_f32_dpp v231, v231, v231 row_half_mirror row_mask:0xf bank_mask:0x5
	v_add_f32_dpp v228, v232, v232 row_half_mirror row_mask:0xf bank_mask:0xa
	v_add_f32_dpp v229, v233, v233 row_half_mirror row_mask:0xf bank_mask:0xa
	v_add_f32_dpp v230, v234, v234 row_half_mirror row_mask:0xf bank_mask:0xa
	v_add_f32_dpp v231, v235, v235 row_half_mirror row_mask:0xf bank_mask:0xa
	v_add_f32_dpp v244, v228, v228 quad_perm:[2,3,0,1] row_mask:0xf bank_mask:0xf
	v_add_f32_dpp v245, v229, v229 quad_perm:[2,3,0,1] row_mask:0xf bank_mask:0xf
	v_add_f32_dpp v246, v230, v230 quad_perm:[2,3,0,1] row_mask:0xf bank_mask:0xf
	v_add_f32_dpp v247, v231, v231 quad_perm:[2,3,0,1] row_mask:0xf bank_mask:0xf
	v_cndmask_b32_e64 v228, v244, v246, s[48:49]
	v_cndmask_b32_e64 v229, v245, v247, s[48:49]
	s_nop 0
	v_add_f32_dpp v244, v228, v228 quad_perm:[1,0,3,2] row_mask:0xf bank_mask:0xf
	v_add_f32_dpp v245, v229, v229 quad_perm:[1,0,3,2] row_mask:0xf bank_mask:0xf
	v_cndmask_b32_e64 v2, v244, v245, s[50:51]
	v_mul_f32_e32 v228, v71, v99
	v_mul_f32_e32 v229, v67, v99
	v_mul_f32_e32 v230, v63, v99
	v_mul_f32_e32 v231, v59, v99
	v_fmac_f32_e32 v228, v70, v91
	v_fmac_f32_e32 v229, v66, v91
	v_fmac_f32_e32 v230, v62, v91
	v_fmac_f32_e32 v231, v58, v91
	v_fmac_f32_e32 v228, v72, v108
	v_fmac_f32_e32 v229, v68, v108
	v_fmac_f32_e32 v230, v64, v108
	v_fmac_f32_e32 v231, v60, v108
	v_fmac_f32_e32 v228, v73, v109
	v_fmac_f32_e32 v229, v69, v109
	v_fmac_f32_e32 v230, v65, v109
	v_fmac_f32_e32 v231, v61, v109
	v_mul_f32_e32 v232, v55, v99
	v_mul_f32_e32 v233, v51, v99
	v_mul_f32_e32 v234, v47, v99
	v_mul_f32_e32 v235, v43, v99
	v_fmac_f32_e32 v232, v54, v91
	v_fmac_f32_e32 v233, v50, v91
	v_fmac_f32_e32 v234, v46, v91
	v_fmac_f32_e32 v235, v42, v91
	v_fmac_f32_e32 v232, v56, v108
	v_fmac_f32_e32 v233, v52, v108
	v_fmac_f32_e32 v234, v48, v108
	v_fmac_f32_e32 v235, v44, v108
	v_fmac_f32_e32 v232, v57, v109
	v_fmac_f32_e32 v233, v53, v109
	v_fmac_f32_e32 v234, v49, v109
	v_fmac_f32_e32 v235, v45, v109
	v_mul_f32_e32 v236, v39, v99
	v_mul_f32_e32 v237, v35, v99
	v_mul_f32_e32 v238, v31, v99
	v_mul_f32_e32 v239, v27, v99
	v_fmac_f32_e32 v236, v38, v91
	v_fmac_f32_e32 v237, v34, v91
	v_fmac_f32_e32 v238, v30, v91
	v_fmac_f32_e32 v239, v26, v91
	v_fmac_f32_e32 v236, v40, v108
	v_fmac_f32_e32 v237, v36, v108
	v_fmac_f32_e32 v238, v32, v108
	v_fmac_f32_e32 v239, v28, v108
	v_fmac_f32_e32 v236, v41, v109
	v_fmac_f32_e32 v237, v37, v109
	v_fmac_f32_e32 v238, v33, v109
	v_fmac_f32_e32 v239, v29, v109
	v_mul_f32_e32 v240, v23, v99
	v_mul_f32_e32 v241, v19, v99
	v_mul_f32_e32 v242, v15, v99
	v_mul_f32_e32 v243, v11, v99
	v_fmac_f32_e32 v240, v22, v91
	v_fmac_f32_e32 v241, v18, v91
	v_fmac_f32_e32 v242, v14, v91
	v_fmac_f32_e32 v243, v10, v91
	v_fmac_f32_e32 v240, v24, v108
	v_fmac_f32_e32 v241, v20, v108
	v_fmac_f32_e32 v242, v16, v108
	v_fmac_f32_e32 v243, v12, v108
	v_fmac_f32_e32 v240, v25, v109
	v_fmac_f32_e32 v241, v21, v109
	v_fmac_f32_e32 v242, v17, v109
	v_fmac_f32_e32 v243, v13, v109
	v_add_f32_dpp v228, v228, v228 row_ror:8 row_mask:0xf bank_mask:0x3
	v_add_f32_dpp v229, v229, v229 row_ror:8 row_mask:0xf bank_mask:0x3
	v_add_f32_dpp v230, v230, v230 row_ror:8 row_mask:0xf bank_mask:0x3
	v_add_f32_dpp v231, v231, v231 row_ror:8 row_mask:0xf bank_mask:0x3
	v_add_f32_dpp v232, v232, v232 row_ror:8 row_mask:0xf bank_mask:0x3
	v_add_f32_dpp v233, v233, v233 row_ror:8 row_mask:0xf bank_mask:0x3
	v_add_f32_dpp v234, v234, v234 row_ror:8 row_mask:0xf bank_mask:0x3
	v_add_f32_dpp v235, v235, v235 row_ror:8 row_mask:0xf bank_mask:0x3
	v_add_f32_dpp v228, v236, v236 row_ror:8 row_mask:0xf bank_mask:0xc
	v_add_f32_dpp v229, v237, v237 row_ror:8 row_mask:0xf bank_mask:0xc
	v_add_f32_dpp v230, v238, v238 row_ror:8 row_mask:0xf bank_mask:0xc
	v_add_f32_dpp v231, v239, v239 row_ror:8 row_mask:0xf bank_mask:0xc
	v_add_f32_dpp v232, v240, v240 row_ror:8 row_mask:0xf bank_mask:0xc
	v_add_f32_dpp v233, v241, v241 row_ror:8 row_mask:0xf bank_mask:0xc
	v_add_f32_dpp v234, v242, v242 row_ror:8 row_mask:0xf bank_mask:0xc
	v_add_f32_dpp v235, v243, v243 row_ror:8 row_mask:0xf bank_mask:0xc
	v_add_f32_dpp v228, v228, v228 row_half_mirror row_mask:0xf bank_mask:0x5
	v_add_f32_dpp v229, v229, v229 row_half_mirror row_mask:0xf bank_mask:0x5
	v_add_f32_dpp v230, v230, v230 row_half_mirror row_mask:0xf bank_mask:0x5
	v_add_f32_dpp v231, v231, v231 row_half_mirror row_mask:0xf bank_mask:0x5
	v_add_f32_dpp v228, v232, v232 row_half_mirror row_mask:0xf bank_mask:0xa
	v_add_f32_dpp v229, v233, v233 row_half_mirror row_mask:0xf bank_mask:0xa
	v_add_f32_dpp v230, v234, v234 row_half_mirror row_mask:0xf bank_mask:0xa
	v_add_f32_dpp v231, v235, v235 row_half_mirror row_mask:0xf bank_mask:0xa
	v_add_f32_dpp v244, v228, v228 quad_perm:[2,3,0,1] row_mask:0xf bank_mask:0xf
	v_add_f32_dpp v245, v229, v229 quad_perm:[2,3,0,1] row_mask:0xf bank_mask:0xf
	v_add_f32_dpp v246, v230, v230 quad_perm:[2,3,0,1] row_mask:0xf bank_mask:0xf
	v_add_f32_dpp v247, v231, v231 quad_perm:[2,3,0,1] row_mask:0xf bank_mask:0xf
	v_cndmask_b32_e64 v228, v244, v246, s[48:49]
	v_cndmask_b32_e64 v229, v245, v247, s[48:49]
	s_nop 0
	v_add_f32_dpp v244, v228, v228 quad_perm:[1,0,3,2] row_mask:0xf bank_mask:0xf
	v_add_f32_dpp v245, v229, v229 quad_perm:[1,0,3,2] row_mask:0xf bank_mask:0xf
	v_cndmask_b32_e64 v4, v244, v245, s[50:51]
	v_mul_f32_e32 v228, v71, v111
	v_mul_f32_e32 v229, v67, v111
	v_mul_f32_e32 v230, v63, v111
	v_mul_f32_e32 v231, v59, v111
	v_fmac_f32_e32 v228, v70, v110
	v_fmac_f32_e32 v229, v66, v110
	v_fmac_f32_e32 v230, v62, v110
	v_fmac_f32_e32 v231, v58, v110
	v_fmac_f32_e32 v228, v72, v112
	v_fmac_f32_e32 v229, v68, v112
	v_fmac_f32_e32 v230, v64, v112
	v_fmac_f32_e32 v231, v60, v112
	v_fmac_f32_e32 v228, v73, v113
	v_fmac_f32_e32 v229, v69, v113
	v_fmac_f32_e32 v230, v65, v113
	v_fmac_f32_e32 v231, v61, v113
	v_mul_f32_e32 v232, v55, v111
	v_mul_f32_e32 v233, v51, v111
	v_mul_f32_e32 v234, v47, v111
	v_mul_f32_e32 v235, v43, v111
	v_fmac_f32_e32 v232, v54, v110
	v_fmac_f32_e32 v233, v50, v110
	v_fmac_f32_e32 v234, v46, v110
	v_fmac_f32_e32 v235, v42, v110
	v_fmac_f32_e32 v232, v56, v112
	v_fmac_f32_e32 v233, v52, v112
	v_fmac_f32_e32 v234, v48, v112
	v_fmac_f32_e32 v235, v44, v112
	v_fmac_f32_e32 v232, v57, v113
	v_fmac_f32_e32 v233, v53, v113
	v_fmac_f32_e32 v234, v49, v113
	v_fmac_f32_e32 v235, v45, v113
	v_mul_f32_e32 v236, v39, v111
	v_mul_f32_e32 v237, v35, v111
	v_mul_f32_e32 v238, v31, v111
	v_mul_f32_e32 v239, v27, v111
	v_fmac_f32_e32 v236, v38, v110
	v_fmac_f32_e32 v237, v34, v110
	v_fmac_f32_e32 v238, v30, v110
	v_fmac_f32_e32 v239, v26, v110
	v_fmac_f32_e32 v236, v40, v112
	v_fmac_f32_e32 v237, v36, v112
	v_fmac_f32_e32 v238, v32, v112
	v_fmac_f32_e32 v239, v28, v112
	v_fmac_f32_e32 v236, v41, v113
	v_fmac_f32_e32 v237, v37, v113
	v_fmac_f32_e32 v238, v33, v113
	v_fmac_f32_e32 v239, v29, v113
	v_mul_f32_e32 v240, v23, v111
	v_mul_f32_e32 v241, v19, v111
	v_mul_f32_e32 v242, v15, v111
	v_mul_f32_e32 v243, v11, v111
	v_fmac_f32_e32 v240, v22, v110
	v_fmac_f32_e32 v241, v18, v110
	v_fmac_f32_e32 v242, v14, v110
	v_fmac_f32_e32 v243, v10, v110
	v_fmac_f32_e32 v240, v24, v112
	v_fmac_f32_e32 v241, v20, v112
	v_fmac_f32_e32 v242, v16, v112
	v_fmac_f32_e32 v243, v12, v112
	v_fmac_f32_e32 v240, v25, v113
	v_fmac_f32_e32 v241, v21, v113
	v_fmac_f32_e32 v242, v17, v113
	v_fmac_f32_e32 v243, v13, v113
	v_add_f32_dpp v228, v228, v228 row_ror:8 row_mask:0xf bank_mask:0x3
	v_add_f32_dpp v229, v229, v229 row_ror:8 row_mask:0xf bank_mask:0x3
	v_add_f32_dpp v230, v230, v230 row_ror:8 row_mask:0xf bank_mask:0x3
	v_add_f32_dpp v231, v231, v231 row_ror:8 row_mask:0xf bank_mask:0x3
	v_add_f32_dpp v232, v232, v232 row_ror:8 row_mask:0xf bank_mask:0x3
	v_add_f32_dpp v233, v233, v233 row_ror:8 row_mask:0xf bank_mask:0x3
	v_add_f32_dpp v234, v234, v234 row_ror:8 row_mask:0xf bank_mask:0x3
	v_add_f32_dpp v235, v235, v235 row_ror:8 row_mask:0xf bank_mask:0x3
	v_add_f32_dpp v228, v236, v236 row_ror:8 row_mask:0xf bank_mask:0xc
	v_add_f32_dpp v229, v237, v237 row_ror:8 row_mask:0xf bank_mask:0xc
	v_add_f32_dpp v230, v238, v238 row_ror:8 row_mask:0xf bank_mask:0xc
	v_add_f32_dpp v231, v239, v239 row_ror:8 row_mask:0xf bank_mask:0xc
	v_add_f32_dpp v232, v240, v240 row_ror:8 row_mask:0xf bank_mask:0xc
	v_add_f32_dpp v233, v241, v241 row_ror:8 row_mask:0xf bank_mask:0xc
	v_add_f32_dpp v234, v242, v242 row_ror:8 row_mask:0xf bank_mask:0xc
	v_add_f32_dpp v235, v243, v243 row_ror:8 row_mask:0xf bank_mask:0xc
	v_add_f32_dpp v228, v228, v228 row_half_mirror row_mask:0xf bank_mask:0x5
	v_add_f32_dpp v229, v229, v229 row_half_mirror row_mask:0xf bank_mask:0x5
	v_add_f32_dpp v230, v230, v230 row_half_mirror row_mask:0xf bank_mask:0x5
	v_add_f32_dpp v231, v231, v231 row_half_mirror row_mask:0xf bank_mask:0x5
	v_add_f32_dpp v228, v232, v232 row_half_mirror row_mask:0xf bank_mask:0xa
	v_add_f32_dpp v229, v233, v233 row_half_mirror row_mask:0xf bank_mask:0xa
	v_add_f32_dpp v230, v234, v234 row_half_mirror row_mask:0xf bank_mask:0xa
	v_add_f32_dpp v231, v235, v235 row_half_mirror row_mask:0xf bank_mask:0xa
	v_add_f32_dpp v244, v228, v228 quad_perm:[2,3,0,1] row_mask:0xf bank_mask:0xf
	v_add_f32_dpp v245, v229, v229 quad_perm:[2,3,0,1] row_mask:0xf bank_mask:0xf
	v_add_f32_dpp v246, v230, v230 quad_perm:[2,3,0,1] row_mask:0xf bank_mask:0xf
	v_add_f32_dpp v247, v231, v231 quad_perm:[2,3,0,1] row_mask:0xf bank_mask:0xf
	v_cndmask_b32_e64 v228, v244, v246, s[48:49]
	v_cndmask_b32_e64 v229, v245, v247, s[48:49]
	s_nop 0
	v_add_f32_dpp v244, v228, v228 quad_perm:[1,0,3,2] row_mask:0xf bank_mask:0xf
	v_add_f32_dpp v245, v229, v229 quad_perm:[1,0,3,2] row_mask:0xf bank_mask:0xf
	v_cndmask_b32_e64 v6, v244, v245, s[50:51]
	v_mul_f32_e32 v228, v71, v115
	v_mul_f32_e32 v229, v67, v115
	v_mul_f32_e32 v230, v63, v115
	v_mul_f32_e32 v231, v59, v115
	v_fmac_f32_e32 v228, v70, v114
	v_fmac_f32_e32 v229, v66, v114
	v_fmac_f32_e32 v230, v62, v114
	v_fmac_f32_e32 v231, v58, v114
	v_fmac_f32_e32 v228, v72, v116
	v_fmac_f32_e32 v229, v68, v116
	v_fmac_f32_e32 v230, v64, v116
	v_fmac_f32_e32 v231, v60, v116
	v_fmac_f32_e32 v228, v73, v117
	v_fmac_f32_e32 v229, v69, v117
	v_fmac_f32_e32 v230, v65, v117
	v_fmac_f32_e32 v231, v61, v117
	v_mul_f32_e32 v232, v55, v115
	v_mul_f32_e32 v233, v51, v115
	v_mul_f32_e32 v234, v47, v115
	v_mul_f32_e32 v235, v43, v115
	v_fmac_f32_e32 v232, v54, v114
	v_fmac_f32_e32 v233, v50, v114
	v_fmac_f32_e32 v234, v46, v114
	v_fmac_f32_e32 v235, v42, v114
	v_fmac_f32_e32 v232, v56, v116
	v_fmac_f32_e32 v233, v52, v116
	v_fmac_f32_e32 v234, v48, v116
	v_fmac_f32_e32 v235, v44, v116
	v_fmac_f32_e32 v232, v57, v117
	v_fmac_f32_e32 v233, v53, v117
	v_fmac_f32_e32 v234, v49, v117
	v_fmac_f32_e32 v235, v45, v117
	v_mul_f32_e32 v236, v39, v115
	v_mul_f32_e32 v237, v35, v115
	v_mul_f32_e32 v238, v31, v115
	v_mul_f32_e32 v239, v27, v115
	v_fmac_f32_e32 v236, v38, v114
	v_fmac_f32_e32 v237, v34, v114
	v_fmac_f32_e32 v238, v30, v114
	v_fmac_f32_e32 v239, v26, v114
	v_fmac_f32_e32 v236, v40, v116
	v_fmac_f32_e32 v237, v36, v116
	v_fmac_f32_e32 v238, v32, v116
	v_fmac_f32_e32 v239, v28, v116
	v_fmac_f32_e32 v236, v41, v117
	v_fmac_f32_e32 v237, v37, v117
	v_fmac_f32_e32 v238, v33, v117
	v_fmac_f32_e32 v239, v29, v117
	v_mul_f32_e32 v240, v23, v115
	v_mul_f32_e32 v241, v19, v115
	v_mul_f32_e32 v242, v15, v115
	v_mul_f32_e32 v243, v11, v115
	v_fmac_f32_e32 v240, v22, v114
	v_fmac_f32_e32 v241, v18, v114
	v_fmac_f32_e32 v242, v14, v114
	v_fmac_f32_e32 v243, v10, v114
	v_fmac_f32_e32 v240, v24, v116
	v_fmac_f32_e32 v241, v20, v116
	v_fmac_f32_e32 v242, v16, v116
	v_fmac_f32_e32 v243, v12, v116
	v_fmac_f32_e32 v240, v25, v117
	v_fmac_f32_e32 v241, v21, v117
	v_fmac_f32_e32 v242, v17, v117
	v_fmac_f32_e32 v243, v13, v117
	v_add_f32_dpp v228, v228, v228 row_ror:8 row_mask:0xf bank_mask:0x3
	v_add_f32_dpp v229, v229, v229 row_ror:8 row_mask:0xf bank_mask:0x3
	v_add_f32_dpp v230, v230, v230 row_ror:8 row_mask:0xf bank_mask:0x3
	v_add_f32_dpp v231, v231, v231 row_ror:8 row_mask:0xf bank_mask:0x3
	v_add_f32_dpp v232, v232, v232 row_ror:8 row_mask:0xf bank_mask:0x3
	v_add_f32_dpp v233, v233, v233 row_ror:8 row_mask:0xf bank_mask:0x3
	v_add_f32_dpp v234, v234, v234 row_ror:8 row_mask:0xf bank_mask:0x3
	v_add_f32_dpp v235, v235, v235 row_ror:8 row_mask:0xf bank_mask:0x3
	v_add_f32_dpp v228, v236, v236 row_ror:8 row_mask:0xf bank_mask:0xc
	v_add_f32_dpp v229, v237, v237 row_ror:8 row_mask:0xf bank_mask:0xc
	v_add_f32_dpp v230, v238, v238 row_ror:8 row_mask:0xf bank_mask:0xc
	v_add_f32_dpp v231, v239, v239 row_ror:8 row_mask:0xf bank_mask:0xc
	v_add_f32_dpp v232, v240, v240 row_ror:8 row_mask:0xf bank_mask:0xc
	v_add_f32_dpp v233, v241, v241 row_ror:8 row_mask:0xf bank_mask:0xc
	v_add_f32_dpp v234, v242, v242 row_ror:8 row_mask:0xf bank_mask:0xc
	v_add_f32_dpp v235, v243, v243 row_ror:8 row_mask:0xf bank_mask:0xc
	v_add_f32_dpp v228, v228, v228 row_half_mirror row_mask:0xf bank_mask:0x5
	v_add_f32_dpp v229, v229, v229 row_half_mirror row_mask:0xf bank_mask:0x5
	v_add_f32_dpp v230, v230, v230 row_half_mirror row_mask:0xf bank_mask:0x5
	v_add_f32_dpp v231, v231, v231 row_half_mirror row_mask:0xf bank_mask:0x5
	v_add_f32_dpp v228, v232, v232 row_half_mirror row_mask:0xf bank_mask:0xa
	v_add_f32_dpp v229, v233, v233 row_half_mirror row_mask:0xf bank_mask:0xa
	v_add_f32_dpp v230, v234, v234 row_half_mirror row_mask:0xf bank_mask:0xa
	v_add_f32_dpp v231, v235, v235 row_half_mirror row_mask:0xf bank_mask:0xa
	v_add_f32_dpp v244, v228, v228 quad_perm:[2,3,0,1] row_mask:0xf bank_mask:0xf
	v_add_f32_dpp v245, v229, v229 quad_perm:[2,3,0,1] row_mask:0xf bank_mask:0xf
	v_add_f32_dpp v246, v230, v230 quad_perm:[2,3,0,1] row_mask:0xf bank_mask:0xf
	v_add_f32_dpp v247, v231, v231 quad_perm:[2,3,0,1] row_mask:0xf bank_mask:0xf
	v_cndmask_b32_e64 v228, v244, v246, s[48:49]
	v_cndmask_b32_e64 v229, v245, v247, s[48:49]
	s_nop 0
	v_add_f32_dpp v244, v228, v228 quad_perm:[1,0,3,2] row_mask:0xf bank_mask:0xf
	v_add_f32_dpp v245, v229, v229 quad_perm:[1,0,3,2] row_mask:0xf bank_mask:0xf
	v_cndmask_b32_e64 v8, v244, v245, s[50:51]
	s_waitcnt vmcnt(12)
	v_mul_f32_e32 v228, v161, v88
	v_mul_f32_e32 v229, v165, v88
	v_mul_f32_e32 v230, v169, v88
	v_mul_f32_e32 v231, v173, v88
	v_fmac_f32_e32 v228, v160, v79
	v_fmac_f32_e32 v229, v164, v79
	v_fmac_f32_e32 v230, v168, v79
	v_fmac_f32_e32 v231, v172, v79
	v_fmac_f32_e32 v228, v162, v89
	v_fmac_f32_e32 v229, v166, v89
	v_fmac_f32_e32 v230, v170, v89
	v_fmac_f32_e32 v231, v174, v89
	v_fmac_f32_e32 v228, v163, v90
	v_fmac_f32_e32 v229, v167, v90
	v_fmac_f32_e32 v230, v171, v90
	v_fmac_f32_e32 v231, v175, v90
	s_waitcnt vmcnt(8)
	v_mul_f32_e32 v232, v177, v88
	v_mul_f32_e32 v233, v181, v88
	v_mul_f32_e32 v234, v185, v88
	v_mul_f32_e32 v235, v189, v88
	v_fmac_f32_e32 v232, v176, v79
	v_fmac_f32_e32 v233, v180, v79
	v_fmac_f32_e32 v234, v184, v79
	v_fmac_f32_e32 v235, v188, v79
	v_fmac_f32_e32 v232, v178, v89
	v_fmac_f32_e32 v233, v182, v89
	v_fmac_f32_e32 v234, v186, v89
	v_fmac_f32_e32 v235, v190, v89
	v_fmac_f32_e32 v232, v179, v90
	v_fmac_f32_e32 v233, v183, v90
	v_fmac_f32_e32 v234, v187, v90
	v_fmac_f32_e32 v235, v191, v90
	s_waitcnt vmcnt(4)
	v_mul_f32_e32 v236, v193, v88
	v_mul_f32_e32 v237, v201, v88
	v_mul_f32_e32 v238, v205, v88
	v_mul_f32_e32 v239, v209, v88
	v_fmac_f32_e32 v236, v192, v79
	v_fmac_f32_e32 v237, v200, v79
	v_fmac_f32_e32 v238, v204, v79
	v_fmac_f32_e32 v239, v208, v79
	v_fmac_f32_e32 v236, v194, v89
	v_fmac_f32_e32 v237, v202, v89
	v_fmac_f32_e32 v238, v206, v89
	v_fmac_f32_e32 v239, v210, v89
	v_fmac_f32_e32 v236, v195, v90
	v_fmac_f32_e32 v237, v203, v90
	v_fmac_f32_e32 v238, v207, v90
	v_fmac_f32_e32 v239, v211, v90
	s_waitcnt vmcnt(0)
	v_mul_f32_e32 v240, v213, v88
	v_mul_f32_e32 v241, v217, v88
	v_mul_f32_e32 v242, v221, v88
	v_mul_f32_e32 v243, v225, v88
	v_fmac_f32_e32 v240, v212, v79
	v_fmac_f32_e32 v241, v216, v79
	v_fmac_f32_e32 v242, v220, v79
	v_fmac_f32_e32 v243, v224, v79
	v_fmac_f32_e32 v240, v214, v89
	v_fmac_f32_e32 v241, v218, v89
	v_fmac_f32_e32 v242, v222, v89
	v_fmac_f32_e32 v243, v226, v89
	v_fmac_f32_e32 v240, v215, v90
	v_fmac_f32_e32 v241, v219, v90
	v_fmac_f32_e32 v242, v223, v90
	v_fmac_f32_e32 v243, v227, v90
	v_add_f32_dpp v228, v228, v228 row_ror:8 row_mask:0xf bank_mask:0x3
	v_add_f32_dpp v229, v229, v229 row_ror:8 row_mask:0xf bank_mask:0x3
	v_add_f32_dpp v230, v230, v230 row_ror:8 row_mask:0xf bank_mask:0x3
	v_add_f32_dpp v231, v231, v231 row_ror:8 row_mask:0xf bank_mask:0x3
	v_add_f32_dpp v232, v232, v232 row_ror:8 row_mask:0xf bank_mask:0x3
	v_add_f32_dpp v233, v233, v233 row_ror:8 row_mask:0xf bank_mask:0x3
	v_add_f32_dpp v234, v234, v234 row_ror:8 row_mask:0xf bank_mask:0x3
	v_add_f32_dpp v235, v235, v235 row_ror:8 row_mask:0xf bank_mask:0x3
	v_add_f32_dpp v228, v236, v236 row_ror:8 row_mask:0xf bank_mask:0xc
	v_add_f32_dpp v229, v237, v237 row_ror:8 row_mask:0xf bank_mask:0xc
	v_add_f32_dpp v230, v238, v238 row_ror:8 row_mask:0xf bank_mask:0xc
	v_add_f32_dpp v231, v239, v239 row_ror:8 row_mask:0xf bank_mask:0xc
	v_add_f32_dpp v232, v240, v240 row_ror:8 row_mask:0xf bank_mask:0xc
	v_add_f32_dpp v233, v241, v241 row_ror:8 row_mask:0xf bank_mask:0xc
	v_add_f32_dpp v234, v242, v242 row_ror:8 row_mask:0xf bank_mask:0xc
	v_add_f32_dpp v235, v243, v243 row_ror:8 row_mask:0xf bank_mask:0xc
	v_add_f32_dpp v228, v228, v228 row_half_mirror row_mask:0xf bank_mask:0x5
	v_add_f32_dpp v229, v229, v229 row_half_mirror row_mask:0xf bank_mask:0x5
	v_add_f32_dpp v230, v230, v230 row_half_mirror row_mask:0xf bank_mask:0x5
	v_add_f32_dpp v231, v231, v231 row_half_mirror row_mask:0xf bank_mask:0x5
	v_add_f32_dpp v228, v232, v232 row_half_mirror row_mask:0xf bank_mask:0xa
	v_add_f32_dpp v229, v233, v233 row_half_mirror row_mask:0xf bank_mask:0xa
	v_add_f32_dpp v230, v234, v234 row_half_mirror row_mask:0xf bank_mask:0xa
	v_add_f32_dpp v231, v235, v235 row_half_mirror row_mask:0xf bank_mask:0xa
	v_add_f32_dpp v244, v228, v228 quad_perm:[2,3,0,1] row_mask:0xf bank_mask:0xf
	v_add_f32_dpp v245, v229, v229 quad_perm:[2,3,0,1] row_mask:0xf bank_mask:0xf
	v_add_f32_dpp v246, v230, v230 quad_perm:[2,3,0,1] row_mask:0xf bank_mask:0xf
	v_add_f32_dpp v247, v231, v231 quad_perm:[2,3,0,1] row_mask:0xf bank_mask:0xf
	v_cndmask_b32_e64 v228, v244, v246, s[48:49]
	v_cndmask_b32_e64 v229, v245, v247, s[48:49]
	s_nop 0
	v_add_f32_dpp v244, v228, v228 quad_perm:[1,0,3,2] row_mask:0xf bank_mask:0xf
	v_add_f32_dpp v245, v229, v229 quad_perm:[1,0,3,2] row_mask:0xf bank_mask:0xf
	v_cndmask_b32_e64 v3, v244, v245, s[50:51]
	v_mul_f32_e32 v228, v161, v99
	v_mul_f32_e32 v229, v165, v99
	v_mul_f32_e32 v230, v169, v99
	v_mul_f32_e32 v231, v173, v99
	v_fmac_f32_e32 v228, v160, v91
	v_fmac_f32_e32 v229, v164, v91
	v_fmac_f32_e32 v230, v168, v91
	v_fmac_f32_e32 v231, v172, v91
	v_fmac_f32_e32 v228, v162, v108
	v_fmac_f32_e32 v229, v166, v108
	v_fmac_f32_e32 v230, v170, v108
	v_fmac_f32_e32 v231, v174, v108
	v_fmac_f32_e32 v228, v163, v109
	v_fmac_f32_e32 v229, v167, v109
	v_fmac_f32_e32 v230, v171, v109
	v_fmac_f32_e32 v231, v175, v109
	v_mul_f32_e32 v232, v177, v99
	v_mul_f32_e32 v233, v181, v99
	v_mul_f32_e32 v234, v185, v99
	v_mul_f32_e32 v235, v189, v99
	v_fmac_f32_e32 v232, v176, v91
	v_fmac_f32_e32 v233, v180, v91
	v_fmac_f32_e32 v234, v184, v91
	v_fmac_f32_e32 v235, v188, v91
	v_fmac_f32_e32 v232, v178, v108
	v_fmac_f32_e32 v233, v182, v108
	v_fmac_f32_e32 v234, v186, v108
	v_fmac_f32_e32 v235, v190, v108
	v_fmac_f32_e32 v232, v179, v109
	v_fmac_f32_e32 v233, v183, v109
	v_fmac_f32_e32 v234, v187, v109
	v_fmac_f32_e32 v235, v191, v109
	v_mul_f32_e32 v236, v193, v99
	v_mul_f32_e32 v237, v201, v99
	v_mul_f32_e32 v238, v205, v99
	v_mul_f32_e32 v239, v209, v99
	v_fmac_f32_e32 v236, v192, v91
	v_fmac_f32_e32 v237, v200, v91
	v_fmac_f32_e32 v238, v204, v91
	v_fmac_f32_e32 v239, v208, v91
	v_fmac_f32_e32 v236, v194, v108
	v_fmac_f32_e32 v237, v202, v108
	v_fmac_f32_e32 v238, v206, v108
	v_fmac_f32_e32 v239, v210, v108
	v_fmac_f32_e32 v236, v195, v109
	v_fmac_f32_e32 v237, v203, v109
	v_fmac_f32_e32 v238, v207, v109
	v_fmac_f32_e32 v239, v211, v109
	v_mul_f32_e32 v240, v213, v99
	v_mul_f32_e32 v241, v217, v99
	v_mul_f32_e32 v242, v221, v99
	v_mul_f32_e32 v243, v225, v99
	v_fmac_f32_e32 v240, v212, v91
	v_fmac_f32_e32 v241, v216, v91
	v_fmac_f32_e32 v242, v220, v91
	v_fmac_f32_e32 v243, v224, v91
	v_fmac_f32_e32 v240, v214, v108
	v_fmac_f32_e32 v241, v218, v108
	v_fmac_f32_e32 v242, v222, v108
	v_fmac_f32_e32 v243, v226, v108
	v_fmac_f32_e32 v240, v215, v109
	v_fmac_f32_e32 v241, v219, v109
	v_fmac_f32_e32 v242, v223, v109
	v_fmac_f32_e32 v243, v227, v109
	v_add_f32_dpp v228, v228, v228 row_ror:8 row_mask:0xf bank_mask:0x3
	v_add_f32_dpp v229, v229, v229 row_ror:8 row_mask:0xf bank_mask:0x3
	v_add_f32_dpp v230, v230, v230 row_ror:8 row_mask:0xf bank_mask:0x3
	v_add_f32_dpp v231, v231, v231 row_ror:8 row_mask:0xf bank_mask:0x3
	v_add_f32_dpp v232, v232, v232 row_ror:8 row_mask:0xf bank_mask:0x3
	v_add_f32_dpp v233, v233, v233 row_ror:8 row_mask:0xf bank_mask:0x3
	v_add_f32_dpp v234, v234, v234 row_ror:8 row_mask:0xf bank_mask:0x3
	v_add_f32_dpp v235, v235, v235 row_ror:8 row_mask:0xf bank_mask:0x3
	v_add_f32_dpp v228, v236, v236 row_ror:8 row_mask:0xf bank_mask:0xc
	v_add_f32_dpp v229, v237, v237 row_ror:8 row_mask:0xf bank_mask:0xc
	v_add_f32_dpp v230, v238, v238 row_ror:8 row_mask:0xf bank_mask:0xc
	v_add_f32_dpp v231, v239, v239 row_ror:8 row_mask:0xf bank_mask:0xc
	v_add_f32_dpp v232, v240, v240 row_ror:8 row_mask:0xf bank_mask:0xc
	v_add_f32_dpp v233, v241, v241 row_ror:8 row_mask:0xf bank_mask:0xc
	v_add_f32_dpp v234, v242, v242 row_ror:8 row_mask:0xf bank_mask:0xc
	v_add_f32_dpp v235, v243, v243 row_ror:8 row_mask:0xf bank_mask:0xc
	v_add_f32_dpp v228, v228, v228 row_half_mirror row_mask:0xf bank_mask:0x5
	v_add_f32_dpp v229, v229, v229 row_half_mirror row_mask:0xf bank_mask:0x5
	v_add_f32_dpp v230, v230, v230 row_half_mirror row_mask:0xf bank_mask:0x5
	v_add_f32_dpp v231, v231, v231 row_half_mirror row_mask:0xf bank_mask:0x5
	v_add_f32_dpp v228, v232, v232 row_half_mirror row_mask:0xf bank_mask:0xa
	v_add_f32_dpp v229, v233, v233 row_half_mirror row_mask:0xf bank_mask:0xa
	v_add_f32_dpp v230, v234, v234 row_half_mirror row_mask:0xf bank_mask:0xa
	v_add_f32_dpp v231, v235, v235 row_half_mirror row_mask:0xf bank_mask:0xa
	v_add_f32_dpp v244, v228, v228 quad_perm:[2,3,0,1] row_mask:0xf bank_mask:0xf
	v_add_f32_dpp v245, v229, v229 quad_perm:[2,3,0,1] row_mask:0xf bank_mask:0xf
	v_add_f32_dpp v246, v230, v230 quad_perm:[2,3,0,1] row_mask:0xf bank_mask:0xf
	v_add_f32_dpp v247, v231, v231 quad_perm:[2,3,0,1] row_mask:0xf bank_mask:0xf
	v_cndmask_b32_e64 v228, v244, v246, s[48:49]
	v_cndmask_b32_e64 v229, v245, v247, s[48:49]
	s_nop 0
	v_add_f32_dpp v244, v228, v228 quad_perm:[1,0,3,2] row_mask:0xf bank_mask:0xf
	v_add_f32_dpp v245, v229, v229 quad_perm:[1,0,3,2] row_mask:0xf bank_mask:0xf
	v_cndmask_b32_e64 v5, v244, v245, s[50:51]
	v_mul_f32_e32 v228, v161, v111
	v_mul_f32_e32 v229, v165, v111
	v_mul_f32_e32 v230, v169, v111
	v_mul_f32_e32 v231, v173, v111
	v_fmac_f32_e32 v228, v160, v110
	v_fmac_f32_e32 v229, v164, v110
	v_fmac_f32_e32 v230, v168, v110
	v_fmac_f32_e32 v231, v172, v110
	v_fmac_f32_e32 v228, v162, v112
	v_fmac_f32_e32 v229, v166, v112
	v_fmac_f32_e32 v230, v170, v112
	v_fmac_f32_e32 v231, v174, v112
	v_fmac_f32_e32 v228, v163, v113
	v_fmac_f32_e32 v229, v167, v113
	v_fmac_f32_e32 v230, v171, v113
	v_fmac_f32_e32 v231, v175, v113
	v_mul_f32_e32 v232, v177, v111
	v_mul_f32_e32 v233, v181, v111
	v_mul_f32_e32 v234, v185, v111
	v_mul_f32_e32 v235, v189, v111
	v_fmac_f32_e32 v232, v176, v110
	v_fmac_f32_e32 v233, v180, v110
	v_fmac_f32_e32 v234, v184, v110
	v_fmac_f32_e32 v235, v188, v110
	v_fmac_f32_e32 v232, v178, v112
	v_fmac_f32_e32 v233, v182, v112
	v_fmac_f32_e32 v234, v186, v112
	v_fmac_f32_e32 v235, v190, v112
	v_fmac_f32_e32 v232, v179, v113
	v_fmac_f32_e32 v233, v183, v113
	v_fmac_f32_e32 v234, v187, v113
	v_fmac_f32_e32 v235, v191, v113
	v_mul_f32_e32 v236, v193, v111
	v_mul_f32_e32 v237, v201, v111
	v_mul_f32_e32 v238, v205, v111
	v_mul_f32_e32 v239, v209, v111
	v_fmac_f32_e32 v236, v192, v110
	v_fmac_f32_e32 v237, v200, v110
	v_fmac_f32_e32 v238, v204, v110
	v_fmac_f32_e32 v239, v208, v110
	v_fmac_f32_e32 v236, v194, v112
	v_fmac_f32_e32 v237, v202, v112
	v_fmac_f32_e32 v238, v206, v112
	v_fmac_f32_e32 v239, v210, v112
	v_fmac_f32_e32 v236, v195, v113
	v_fmac_f32_e32 v237, v203, v113
	v_fmac_f32_e32 v238, v207, v113
	v_fmac_f32_e32 v239, v211, v113
	v_mul_f32_e32 v240, v213, v111
	v_mul_f32_e32 v241, v217, v111
	v_mul_f32_e32 v242, v221, v111
	v_mul_f32_e32 v243, v225, v111
	v_fmac_f32_e32 v240, v212, v110
	v_fmac_f32_e32 v241, v216, v110
	v_fmac_f32_e32 v242, v220, v110
	v_fmac_f32_e32 v243, v224, v110
	v_fmac_f32_e32 v240, v214, v112
	v_fmac_f32_e32 v241, v218, v112
	v_fmac_f32_e32 v242, v222, v112
	v_fmac_f32_e32 v243, v226, v112
	v_fmac_f32_e32 v240, v215, v113
	v_fmac_f32_e32 v241, v219, v113
	v_fmac_f32_e32 v242, v223, v113
	v_fmac_f32_e32 v243, v227, v113
	v_add_f32_dpp v228, v228, v228 row_ror:8 row_mask:0xf bank_mask:0x3
	v_add_f32_dpp v229, v229, v229 row_ror:8 row_mask:0xf bank_mask:0x3
	v_add_f32_dpp v230, v230, v230 row_ror:8 row_mask:0xf bank_mask:0x3
	v_add_f32_dpp v231, v231, v231 row_ror:8 row_mask:0xf bank_mask:0x3
	v_add_f32_dpp v232, v232, v232 row_ror:8 row_mask:0xf bank_mask:0x3
	v_add_f32_dpp v233, v233, v233 row_ror:8 row_mask:0xf bank_mask:0x3
	v_add_f32_dpp v234, v234, v234 row_ror:8 row_mask:0xf bank_mask:0x3
	v_add_f32_dpp v235, v235, v235 row_ror:8 row_mask:0xf bank_mask:0x3
	v_add_f32_dpp v228, v236, v236 row_ror:8 row_mask:0xf bank_mask:0xc
	v_add_f32_dpp v229, v237, v237 row_ror:8 row_mask:0xf bank_mask:0xc
	v_add_f32_dpp v230, v238, v238 row_ror:8 row_mask:0xf bank_mask:0xc
	v_add_f32_dpp v231, v239, v239 row_ror:8 row_mask:0xf bank_mask:0xc
	v_add_f32_dpp v232, v240, v240 row_ror:8 row_mask:0xf bank_mask:0xc
	v_add_f32_dpp v233, v241, v241 row_ror:8 row_mask:0xf bank_mask:0xc
	v_add_f32_dpp v234, v242, v242 row_ror:8 row_mask:0xf bank_mask:0xc
	v_add_f32_dpp v235, v243, v243 row_ror:8 row_mask:0xf bank_mask:0xc
	v_add_f32_dpp v228, v228, v228 row_half_mirror row_mask:0xf bank_mask:0x5
	v_add_f32_dpp v229, v229, v229 row_half_mirror row_mask:0xf bank_mask:0x5
	v_add_f32_dpp v230, v230, v230 row_half_mirror row_mask:0xf bank_mask:0x5
	v_add_f32_dpp v231, v231, v231 row_half_mirror row_mask:0xf bank_mask:0x5
	v_add_f32_dpp v228, v232, v232 row_half_mirror row_mask:0xf bank_mask:0xa
	v_add_f32_dpp v229, v233, v233 row_half_mirror row_mask:0xf bank_mask:0xa
	v_add_f32_dpp v230, v234, v234 row_half_mirror row_mask:0xf bank_mask:0xa
	v_add_f32_dpp v231, v235, v235 row_half_mirror row_mask:0xf bank_mask:0xa
	v_add_f32_dpp v244, v228, v228 quad_perm:[2,3,0,1] row_mask:0xf bank_mask:0xf
	v_add_f32_dpp v245, v229, v229 quad_perm:[2,3,0,1] row_mask:0xf bank_mask:0xf
	v_add_f32_dpp v246, v230, v230 quad_perm:[2,3,0,1] row_mask:0xf bank_mask:0xf
	v_add_f32_dpp v247, v231, v231 quad_perm:[2,3,0,1] row_mask:0xf bank_mask:0xf
	v_cndmask_b32_e64 v228, v244, v246, s[48:49]
	v_cndmask_b32_e64 v229, v245, v247, s[48:49]
	s_nop 0
	v_add_f32_dpp v244, v228, v228 quad_perm:[1,0,3,2] row_mask:0xf bank_mask:0xf
	v_add_f32_dpp v245, v229, v229 quad_perm:[1,0,3,2] row_mask:0xf bank_mask:0xf
	v_cndmask_b32_e64 v7, v244, v245, s[50:51]
	v_mul_f32_e32 v228, v161, v115
	v_mul_f32_e32 v229, v165, v115
	v_mul_f32_e32 v230, v169, v115
	v_mul_f32_e32 v231, v173, v115
	v_fmac_f32_e32 v228, v160, v114
	v_fmac_f32_e32 v229, v164, v114
	v_fmac_f32_e32 v230, v168, v114
	v_fmac_f32_e32 v231, v172, v114
	v_fmac_f32_e32 v228, v162, v116
	v_fmac_f32_e32 v229, v166, v116
	v_fmac_f32_e32 v230, v170, v116
	v_fmac_f32_e32 v231, v174, v116
	v_fmac_f32_e32 v228, v163, v117
	v_fmac_f32_e32 v229, v167, v117
	v_fmac_f32_e32 v230, v171, v117
	v_fmac_f32_e32 v231, v175, v117
	v_mul_f32_e32 v232, v177, v115
	v_mul_f32_e32 v233, v181, v115
	v_mul_f32_e32 v234, v185, v115
	v_mul_f32_e32 v235, v189, v115
	v_fmac_f32_e32 v232, v176, v114
	v_fmac_f32_e32 v233, v180, v114
	v_fmac_f32_e32 v234, v184, v114
	v_fmac_f32_e32 v235, v188, v114
	v_fmac_f32_e32 v232, v178, v116
	v_fmac_f32_e32 v233, v182, v116
	v_fmac_f32_e32 v234, v186, v116
	v_fmac_f32_e32 v235, v190, v116
	v_fmac_f32_e32 v232, v179, v117
	v_fmac_f32_e32 v233, v183, v117
	v_fmac_f32_e32 v234, v187, v117
	v_fmac_f32_e32 v235, v191, v117
	v_mul_f32_e32 v236, v193, v115
	v_mul_f32_e32 v237, v201, v115
	v_mul_f32_e32 v238, v205, v115
	v_mul_f32_e32 v239, v209, v115
	v_fmac_f32_e32 v236, v192, v114
	v_fmac_f32_e32 v237, v200, v114
	v_fmac_f32_e32 v238, v204, v114
	v_fmac_f32_e32 v239, v208, v114
	v_fmac_f32_e32 v236, v194, v116
	v_fmac_f32_e32 v237, v202, v116
	v_fmac_f32_e32 v238, v206, v116
	v_fmac_f32_e32 v239, v210, v116
	v_fmac_f32_e32 v236, v195, v117
	v_fmac_f32_e32 v237, v203, v117
	v_fmac_f32_e32 v238, v207, v117
	v_fmac_f32_e32 v239, v211, v117
	v_mul_f32_e32 v240, v213, v115
	v_mul_f32_e32 v241, v217, v115
	v_mul_f32_e32 v242, v221, v115
	v_mul_f32_e32 v243, v225, v115
	v_fmac_f32_e32 v240, v212, v114
	v_fmac_f32_e32 v241, v216, v114
	v_fmac_f32_e32 v242, v220, v114
	v_fmac_f32_e32 v243, v224, v114
	v_fmac_f32_e32 v240, v214, v116
	v_fmac_f32_e32 v241, v218, v116
	v_fmac_f32_e32 v242, v222, v116
	v_fmac_f32_e32 v243, v226, v116
	v_fmac_f32_e32 v240, v215, v117
	v_fmac_f32_e32 v241, v219, v117
	v_fmac_f32_e32 v242, v223, v117
	v_fmac_f32_e32 v243, v227, v117
	v_add_f32_dpp v228, v228, v228 row_ror:8 row_mask:0xf bank_mask:0x3
	v_add_f32_dpp v229, v229, v229 row_ror:8 row_mask:0xf bank_mask:0x3
	v_add_f32_dpp v230, v230, v230 row_ror:8 row_mask:0xf bank_mask:0x3
	v_add_f32_dpp v231, v231, v231 row_ror:8 row_mask:0xf bank_mask:0x3
	v_add_f32_dpp v232, v232, v232 row_ror:8 row_mask:0xf bank_mask:0x3
	v_add_f32_dpp v233, v233, v233 row_ror:8 row_mask:0xf bank_mask:0x3
	v_add_f32_dpp v234, v234, v234 row_ror:8 row_mask:0xf bank_mask:0x3
	v_add_f32_dpp v235, v235, v235 row_ror:8 row_mask:0xf bank_mask:0x3
	v_add_f32_dpp v228, v236, v236 row_ror:8 row_mask:0xf bank_mask:0xc
	v_add_f32_dpp v229, v237, v237 row_ror:8 row_mask:0xf bank_mask:0xc
	v_add_f32_dpp v230, v238, v238 row_ror:8 row_mask:0xf bank_mask:0xc
	v_add_f32_dpp v231, v239, v239 row_ror:8 row_mask:0xf bank_mask:0xc
	v_add_f32_dpp v232, v240, v240 row_ror:8 row_mask:0xf bank_mask:0xc
	v_add_f32_dpp v233, v241, v241 row_ror:8 row_mask:0xf bank_mask:0xc
	v_add_f32_dpp v234, v242, v242 row_ror:8 row_mask:0xf bank_mask:0xc
	v_add_f32_dpp v235, v243, v243 row_ror:8 row_mask:0xf bank_mask:0xc
	v_add_f32_dpp v228, v228, v228 row_half_mirror row_mask:0xf bank_mask:0x5
	v_add_f32_dpp v229, v229, v229 row_half_mirror row_mask:0xf bank_mask:0x5
	v_add_f32_dpp v230, v230, v230 row_half_mirror row_mask:0xf bank_mask:0x5
	v_add_f32_dpp v231, v231, v231 row_half_mirror row_mask:0xf bank_mask:0x5
	v_add_f32_dpp v228, v232, v232 row_half_mirror row_mask:0xf bank_mask:0xa
	v_add_f32_dpp v229, v233, v233 row_half_mirror row_mask:0xf bank_mask:0xa
	v_add_f32_dpp v230, v234, v234 row_half_mirror row_mask:0xf bank_mask:0xa
	v_add_f32_dpp v231, v235, v235 row_half_mirror row_mask:0xf bank_mask:0xa
	v_add_f32_dpp v244, v228, v228 quad_perm:[2,3,0,1] row_mask:0xf bank_mask:0xf
	v_add_f32_dpp v245, v229, v229 quad_perm:[2,3,0,1] row_mask:0xf bank_mask:0xf
	v_add_f32_dpp v246, v230, v230 quad_perm:[2,3,0,1] row_mask:0xf bank_mask:0xf
	v_add_f32_dpp v247, v231, v231 quad_perm:[2,3,0,1] row_mask:0xf bank_mask:0xf
	v_cndmask_b32_e64 v228, v244, v246, s[48:49]
	v_cndmask_b32_e64 v229, v245, v247, s[48:49]
	s_nop 0
	v_add_f32_dpp v244, v228, v228 quad_perm:[1,0,3,2] row_mask:0xf bank_mask:0xf
	v_add_f32_dpp v245, v229, v229 quad_perm:[1,0,3,2] row_mask:0xf bank_mask:0xf
	v_cndmask_b32_e64 v9, v244, v245, s[50:51]
